# scan: 16-step chunks with producer-staged k*v outer-product rows (waves 4,5), consumer step = 18 instructions, early chunk barrier + next-chunk prefetch, y flush delayed one chunk (ring of 3)
# speedup vs baseline: 1.1016x; 1.0125x over previous
; #define LAS __attribute__((address_space(3)))
; #define RW_LDS_WAIT(X) asm volatile("s_waitcnt lgkmcnt(0)" : "+v"(nk##X), "+v"(dd##X), "+v"(bb##X), "+v"(kp##X), "+v"(rr##X), "+v"(vv##X) :: "memory")
; DI void rwkv_scan_phase(int wv, const Params& P, LAS unsigned char* lds) {
;     ...
;             const int cg = lane & 15, rloc = wave * 4 + (lane >> 4);
;             f32x4 S = (f32x4){0.f, 0.f, 0.f, 0.f};
;             __syncthreads();
;             __builtin_amdgcn_s_setprio(3);
; #pragma unroll 1
;             for (int ck = 0; ck < nck; ++ck) { const int buf = ck & 1;
;                 const LAS float* sb = stg + buf * RW_T * 5 * 64 + 4 * cg; const LAS float* vb = vst + buf * RW_T * 8 + rloc; LAS float* yb = ybuf + buf * RW_T * 128 + wave * 64 + lane;
;                 const unsigned sba = (unsigned)(size_t)sb, vba = (unsigned)(size_t)vb;
;                 f32x4 nkA, ddA, bbA, kpA, rrA, nkB, ddB, bbB, kpB, rrB; float vvA, vvB;
;     ...
;                 f32x2 yacc = (f32x2){0.f, 0.f};
;                 unsigned sbt = sba, vbt = vba; LAS float* ybt = yb;
;                 RW_LDS_LOAD(A, 0); RW_LDS_WAIT(A);
; #pragma unroll 1
;                 for (int tt = 0; tt < RW_T; tt += 16) { sbt = sba + (unsigned)tt * 1280u; vbt = vba + (unsigned)tt * 32u; ybt = yb + tt * 128;
;                     RW_LDS_LOAD(B, 1); RW_STEP(A, 0); RW_LDS_WAIT(B);
;                     RW_LDS_LOAD(A, 2); RW_STEP(B, 1); RW_LDS_WAIT(A);
;                     RW_LDS_LOAD(B, 3); RW_STEP(A, 2); RW_LDS_WAIT(B);
;                     RW_LDS_LOAD(A, 4); RW_STEP(B, 3); RW_LDS_WAIT(A);
.LBB0_3177:
	s_waitcnt lgkmcnt(0)
	s_barrier
	s_and_saveexec_b64 s[20:21], s[2:3]
	s_xor_b64 s[20:21], exec, s[20:21]
	s_cbranch_execz .LBB0_3185
	s_barrier
	s_setprio 3
	v_add_u32_e32 v42, 0xfffec000, v63
	v_mov_b32_e32 v58, 0
	v_mov_b32_e32 v59, 0
	v_lshl_add_u32 v42, v42, 6, v45
	v_mov_b32_e32 v60, 0
	v_mov_b32_e32 v61, 0
	v_add_u32_e32 v42, 0x400, v42
	v_add_u32_e32 v62, 0x3800, v66
	s_mov_b32 s47, 0
	s_mov_b32 s42, 0
	s_lshl_b32 s40, s47, 4
	s_and_b32 s40, s40, 16
	s_mul_i32 s41, s40, 0xc00
	v_add_u32_e32 v74, s41, v45
	v_add_u32_e32 v73, v74, v45
	v_add_u32_e32 v75, s41, v42
	v_add_u32_e32 v72, s42, v62
	s_lshl_b32 s41, s40, 4
	s_add_i32 s41, s41, 0x1e000
	v_add_u32_e32 v40, s41, v45
	ds_read_b128 v[0:3], v73
	ds_read_b128 v[16:19], v73 offset:16
	ds_read_b128 v[4:7], v74 offset:512
	ds_read_b128 v[12:15], v75
	ds_read_b128 v[8:11], v74 offset:768
	ds_read_b128 v[20:23], v73 offset:3072
	ds_read_b128 v[36:39], v73 offset:3088
	ds_read_b128 v[24:27], v74 offset:3584
	ds_read_b128 v[32:35], v75 offset:3072
	ds_read_b128 v[28:31], v74 offset:3840
.Lscan_chunk:
	s_waitcnt lgkmcnt(5)
	v_pk_mul_f32 v[0:1], v[58:59], v[0:1] op_sel_hi:[0,1]
	v_pk_fma_f32 v[0:1], v[58:59], v[2:3], v[0:1] op_sel:[1,0,0] op_sel_hi:[1,1,1]
	v_pk_fma_f32 v[0:1], v[60:61], v[16:17], v[0:1] op_sel_hi:[0,1,1]
	v_pk_fma_f32 v[0:1], v[60:61], v[18:19], v[0:1] op_sel:[1,0,0] op_sel_hi:[1,1,1]
	v_pk_fma_f32 v[12:13], v[58:59], v[4:5], v[12:13]
	v_pk_fma_f32 v[14:15], v[60:61], v[6:7], v[14:15]
	v_add_f32_dpp v0, v0, v0 quad_perm:[1,0,3,2] row_mask:0xf bank_mask:0xf bound_ctrl:1
	ds_read_b128 v[46:49], v73 offset:6144
	ds_read_b128 v[76:79], v73 offset:6160
	v_add_f32_dpp v0, v0, v0 quad_perm:[2,3,0,1] row_mask:0xf bank_mask:0xf bound_ctrl:1
	ds_read_b128 v[50:53], v74 offset:6656
	ds_read_b128 v[68:71], v75 offset:6144
	v_add_f32_dpp v0, v0, v0 row_half_mirror row_mask:0xf bank_mask:0xf bound_ctrl:1
	ds_read_b128 v[54:57], v74 offset:6912
	s_nop 0
	v_add_f32_dpp v0, v0, v0 row_mirror row_mask:0xf bank_mask:0xf bound_ctrl:1
	v_pk_fma_f32 v[58:59], v[8:9], v[0:1], v[12:13] op_sel_hi:[1,0,1]
	v_pk_fma_f32 v[60:61], v[10:11], v[0:1], v[14:15] op_sel_hi:[1,0,1]
	s_waitcnt lgkmcnt(5)
	v_pk_mul_f32 v[20:21], v[58:59], v[20:21] op_sel_hi:[0,1]
	v_pk_fma_f32 v[20:21], v[58:59], v[22:23], v[20:21] op_sel:[1,0,0] op_sel_hi:[1,1,1]
	v_pk_fma_f32 v[20:21], v[60:61], v[36:37], v[20:21] op_sel_hi:[0,1,1]
	v_pk_fma_f32 v[20:21], v[60:61], v[38:39], v[20:21] op_sel:[1,0,0] op_sel_hi:[1,1,1]
	v_pk_fma_f32 v[32:33], v[58:59], v[24:25], v[32:33]
	v_pk_fma_f32 v[34:35], v[60:61], v[26:27], v[34:35]
	v_add_f32_dpp v20, v20, v20 quad_perm:[1,0,3,2] row_mask:0xf bank_mask:0xf bound_ctrl:1
	ds_read_b128 v[0:3], v73 offset:9216
	ds_read_b128 v[16:19], v73 offset:9232
	v_add_f32_dpp v20, v20, v20 quad_perm:[2,3,0,1] row_mask:0xf bank_mask:0xf bound_ctrl:1
	ds_read_b128 v[4:7], v74 offset:9728
	ds_read_b128 v[12:15], v75 offset:9216
	v_add_f32_dpp v20, v20, v20 row_half_mirror row_mask:0xf bank_mask:0xf bound_ctrl:1
	ds_read_b128 v[8:11], v74 offset:9984
	ds_write_b32 v72, v21
	v_add_f32_dpp v20, v20, v20 row_mirror row_mask:0xf bank_mask:0xf bound_ctrl:1
	v_pk_fma_f32 v[58:59], v[28:29], v[20:21], v[32:33] op_sel_hi:[1,0,1]
	v_pk_fma_f32 v[60:61], v[30:31], v[20:21], v[34:35] op_sel_hi:[1,0,1]
	s_waitcnt lgkmcnt(6)
	v_pk_mul_f32 v[46:47], v[58:59], v[46:47] op_sel_hi:[0,1]
	v_pk_fma_f32 v[46:47], v[58:59], v[48:49], v[46:47] op_sel:[1,0,0] op_sel_hi:[1,1,1]
	v_pk_fma_f32 v[46:47], v[60:61], v[76:77], v[46:47] op_sel_hi:[0,1,1]
	v_pk_fma_f32 v[46:47], v[60:61], v[78:79], v[46:47] op_sel:[1,0,0] op_sel_hi:[1,1,1]
	v_pk_fma_f32 v[68:69], v[58:59], v[50:51], v[68:69]
	v_pk_fma_f32 v[70:71], v[60:61], v[52:53], v[70:71]
	v_add_f32_dpp v46, v46, v46 quad_perm:[1,0,3,2] row_mask:0xf bank_mask:0xf bound_ctrl:1
	ds_read_b128 v[20:23], v73 offset:12288
	ds_read_b128 v[36:39], v73 offset:12304
	v_add_f32_dpp v46, v46, v46 quad_perm:[2,3,0,1] row_mask:0xf bank_mask:0xf bound_ctrl:1
	ds_read_b128 v[24:27], v74 offset:12800
	ds_read_b128 v[32:35], v75 offset:12288
	v_add_f32_dpp v46, v46, v46 row_half_mirror row_mask:0xf bank_mask:0xf bound_ctrl:1
	ds_read_b128 v[28:31], v74 offset:13056
	ds_write_b32 v72, v47 offset:512
	v_add_f32_dpp v46, v46, v46 row_mirror row_mask:0xf bank_mask:0xf bound_ctrl:1
	v_pk_fma_f32 v[58:59], v[54:55], v[46:47], v[68:69] op_sel_hi:[1,0,1]
	v_pk_fma_f32 v[60:61], v[56:57], v[46:47], v[70:71] op_sel_hi:[1,0,1]
	s_waitcnt lgkmcnt(7)
	v_pk_mul_f32 v[0:1], v[58:59], v[0:1] op_sel_hi:[0,1]
	v_pk_fma_f32 v[0:1], v[58:59], v[2:3], v[0:1] op_sel:[1,0,0] op_sel_hi:[1,1,1]
	v_pk_fma_f32 v[0:1], v[60:61], v[16:17], v[0:1] op_sel_hi:[0,1,1]
	v_pk_fma_f32 v[0:1], v[60:61], v[18:19], v[0:1] op_sel:[1,0,0] op_sel_hi:[1,1,1]
	v_pk_fma_f32 v[12:13], v[58:59], v[4:5], v[12:13]
	v_pk_fma_f32 v[14:15], v[60:61], v[6:7], v[14:15]
	v_add_f32_dpp v0, v0, v0 quad_perm:[1,0,3,2] row_mask:0xf bank_mask:0xf bound_ctrl:1
	ds_read_b128 v[46:49], v73 offset:15360
	ds_read_b128 v[76:79], v73 offset:15376
	v_add_f32_dpp v0, v0, v0 quad_perm:[2,3,0,1] row_mask:0xf bank_mask:0xf bound_ctrl:1
	ds_read_b128 v[50:53], v74 offset:15872
	ds_read_b128 v[68:71], v75 offset:15360
	v_add_f32_dpp v0, v0, v0 row_half_mirror row_mask:0xf bank_mask:0xf bound_ctrl:1
	ds_read_b128 v[54:57], v74 offset:16128
	ds_write_b32 v72, v1 offset:1024
	v_add_f32_dpp v0, v0, v0 row_mirror row_mask:0xf bank_mask:0xf bound_ctrl:1
	v_pk_fma_f32 v[58:59], v[8:9], v[0:1], v[12:13] op_sel_hi:[1,0,1]
	v_pk_fma_f32 v[60:61], v[10:11], v[0:1], v[14:15] op_sel_hi:[1,0,1]
	s_waitcnt lgkmcnt(7)
; #define LAS __attribute__((address_space(3)))
; #define RW_LDS_WAIT(X) asm volatile("s_waitcnt lgkmcnt(0)" : "+v"(nk##X), "+v"(dd##X), "+v"(bb##X), "+v"(kp##X), "+v"(rr##X), "+v"(vv##X) :: "memory")
; DI void rwkv_scan_phase(int wv, const Params& P, LAS unsigned char* lds) {
;     ...
;                 f32x2 yacc = (f32x2){0.f, 0.f};
;                 unsigned sbt = sba, vbt = vba; LAS float* ybt = yb;
;                 RW_LDS_LOAD(A, 0); RW_LDS_WAIT(A);
; #pragma unroll 1
;                 for (int tt = 0; tt < RW_T; tt += 16) { sbt = sba + (unsigned)tt * 1280u; vbt = vba + (unsigned)tt * 32u; ybt = yb + tt * 128;
;                     RW_LDS_LOAD(B, 1); RW_STEP(A, 0); RW_LDS_WAIT(B);
;                     RW_LDS_LOAD(A, 2); RW_STEP(B, 1); RW_LDS_WAIT(A);
;                     RW_LDS_LOAD(B, 3); RW_STEP(A, 2); RW_LDS_WAIT(B);
;                     RW_LDS_LOAD(A, 4); RW_STEP(B, 3); RW_LDS_WAIT(A);
;                     RW_LDS_LOAD(B, 5); RW_STEP(A, 4); RW_LDS_WAIT(B);
;                     RW_LDS_LOAD(A, 6); RW_STEP(B, 5); RW_LDS_WAIT(A);
;                     RW_LDS_LOAD(B, 7); RW_STEP(A, 6); RW_LDS_WAIT(B);
;                     RW_LDS_LOAD(A, 8); RW_STEP(B, 7); RW_LDS_WAIT(A);
;                     RW_LDS_LOAD(B, 9); RW_STEP(A, 8); RW_LDS_WAIT(B);
;                     RW_LDS_LOAD(A, 10); RW_STEP(B, 9); RW_LDS_WAIT(A);
;                     RW_LDS_LOAD(B, 11); RW_STEP(A, 10); RW_LDS_WAIT(B);
;                     RW_LDS_LOAD(A, 12); RW_STEP(B, 11); RW_LDS_WAIT(A);
;                     RW_LDS_LOAD(B, 13); RW_STEP(A, 12); RW_LDS_WAIT(B);
;                     RW_LDS_LOAD(A, 14); RW_STEP(B, 13); RW_LDS_WAIT(A);
;                     RW_LDS_LOAD(B, 15); RW_STEP(A, 14); RW_LDS_WAIT(B);
;                     RW_LDS_LOAD(A, 16); RW_STEP(B, 15); RW_LDS_WAIT(A);
	v_pk_mul_f32 v[20:21], v[58:59], v[20:21] op_sel_hi:[0,1]
	v_pk_fma_f32 v[20:21], v[58:59], v[22:23], v[20:21] op_sel:[1,0,0] op_sel_hi:[1,1,1]
	v_pk_fma_f32 v[20:21], v[60:61], v[36:37], v[20:21] op_sel_hi:[0,1,1]
	v_pk_fma_f32 v[20:21], v[60:61], v[38:39], v[20:21] op_sel:[1,0,0] op_sel_hi:[1,1,1]
	v_pk_fma_f32 v[32:33], v[58:59], v[24:25], v[32:33]
	v_pk_fma_f32 v[34:35], v[60:61], v[26:27], v[34:35]
	v_add_f32_dpp v20, v20, v20 quad_perm:[1,0,3,2] row_mask:0xf bank_mask:0xf bound_ctrl:1
	ds_read_b128 v[0:3], v73 offset:18432
	ds_read_b128 v[16:19], v73 offset:18448
	v_add_f32_dpp v20, v20, v20 quad_perm:[2,3,0,1] row_mask:0xf bank_mask:0xf bound_ctrl:1
	ds_read_b128 v[4:7], v74 offset:18944
	ds_read_b128 v[12:15], v75 offset:18432
	v_add_f32_dpp v20, v20, v20 row_half_mirror row_mask:0xf bank_mask:0xf bound_ctrl:1
	ds_read_b128 v[8:11], v74 offset:19200
	ds_write_b32 v72, v21 offset:1536
	v_add_f32_dpp v20, v20, v20 row_mirror row_mask:0xf bank_mask:0xf bound_ctrl:1
	v_pk_fma_f32 v[58:59], v[28:29], v[20:21], v[32:33] op_sel_hi:[1,0,1]
	v_pk_fma_f32 v[60:61], v[30:31], v[20:21], v[34:35] op_sel_hi:[1,0,1]
	s_waitcnt lgkmcnt(7)
	v_pk_mul_f32 v[46:47], v[58:59], v[46:47] op_sel_hi:[0,1]
	v_pk_fma_f32 v[46:47], v[58:59], v[48:49], v[46:47] op_sel:[1,0,0] op_sel_hi:[1,1,1]
	v_pk_fma_f32 v[46:47], v[60:61], v[76:77], v[46:47] op_sel_hi:[0,1,1]
	v_pk_fma_f32 v[46:47], v[60:61], v[78:79], v[46:47] op_sel:[1,0,0] op_sel_hi:[1,1,1]
	v_pk_fma_f32 v[68:69], v[58:59], v[50:51], v[68:69]
	v_pk_fma_f32 v[70:71], v[60:61], v[52:53], v[70:71]
	v_add_f32_dpp v46, v46, v46 quad_perm:[1,0,3,2] row_mask:0xf bank_mask:0xf bound_ctrl:1
	ds_read_b128 v[20:23], v73 offset:21504
	ds_read_b128 v[36:39], v73 offset:21520
	v_add_f32_dpp v46, v46, v46 quad_perm:[2,3,0,1] row_mask:0xf bank_mask:0xf bound_ctrl:1
	ds_read_b128 v[24:27], v74 offset:22016
	ds_read_b128 v[32:35], v75 offset:21504
	v_add_f32_dpp v46, v46, v46 row_half_mirror row_mask:0xf bank_mask:0xf bound_ctrl:1
	ds_read_b128 v[28:31], v74 offset:22272
	ds_write_b32 v72, v47 offset:2048
	v_add_f32_dpp v46, v46, v46 row_mirror row_mask:0xf bank_mask:0xf bound_ctrl:1
	v_pk_fma_f32 v[58:59], v[54:55], v[46:47], v[68:69] op_sel_hi:[1,0,1]
	v_pk_fma_f32 v[60:61], v[56:57], v[46:47], v[70:71] op_sel_hi:[1,0,1]
	s_waitcnt lgkmcnt(7)
	v_pk_mul_f32 v[0:1], v[58:59], v[0:1] op_sel_hi:[0,1]
	v_pk_fma_f32 v[0:1], v[58:59], v[2:3], v[0:1] op_sel:[1,0,0] op_sel_hi:[1,1,1]
	v_pk_fma_f32 v[0:1], v[60:61], v[16:17], v[0:1] op_sel_hi:[0,1,1]
	v_pk_fma_f32 v[0:1], v[60:61], v[18:19], v[0:1] op_sel:[1,0,0] op_sel_hi:[1,1,1]
	v_pk_fma_f32 v[12:13], v[58:59], v[4:5], v[12:13]
	v_pk_fma_f32 v[14:15], v[60:61], v[6:7], v[14:15]
	v_add_f32_dpp v0, v0, v0 quad_perm:[1,0,3,2] row_mask:0xf bank_mask:0xf bound_ctrl:1
	ds_read_b128 v[46:49], v73 offset:24576
	ds_read_b128 v[76:79], v73 offset:24592
	v_add_f32_dpp v0, v0, v0 quad_perm:[2,3,0,1] row_mask:0xf bank_mask:0xf bound_ctrl:1
	ds_read_b128 v[50:53], v74 offset:25088
	ds_read_b128 v[68:71], v75 offset:24576
	v_add_f32_dpp v0, v0, v0 row_half_mirror row_mask:0xf bank_mask:0xf bound_ctrl:1
	ds_read_b128 v[54:57], v74 offset:25344
	ds_write_b32 v72, v1 offset:2560
	v_add_f32_dpp v0, v0, v0 row_mirror row_mask:0xf bank_mask:0xf bound_ctrl:1
	v_pk_fma_f32 v[58:59], v[8:9], v[0:1], v[12:13] op_sel_hi:[1,0,1]
	v_pk_fma_f32 v[60:61], v[10:11], v[0:1], v[14:15] op_sel_hi:[1,0,1]
	s_waitcnt lgkmcnt(7)
	v_pk_mul_f32 v[20:21], v[58:59], v[20:21] op_sel_hi:[0,1]
	v_pk_fma_f32 v[20:21], v[58:59], v[22:23], v[20:21] op_sel:[1,0,0] op_sel_hi:[1,1,1]
	v_pk_fma_f32 v[20:21], v[60:61], v[36:37], v[20:21] op_sel_hi:[0,1,1]
	v_pk_fma_f32 v[20:21], v[60:61], v[38:39], v[20:21] op_sel:[1,0,0] op_sel_hi:[1,1,1]
	v_pk_fma_f32 v[32:33], v[58:59], v[24:25], v[32:33]
	v_pk_fma_f32 v[34:35], v[60:61], v[26:27], v[34:35]
	v_add_f32_dpp v20, v20, v20 quad_perm:[1,0,3,2] row_mask:0xf bank_mask:0xf bound_ctrl:1
	ds_read_b128 v[0:3], v73 offset:27648
	ds_read_b128 v[16:19], v73 offset:27664
	v_add_f32_dpp v20, v20, v20 quad_perm:[2,3,0,1] row_mask:0xf bank_mask:0xf bound_ctrl:1
	ds_read_b128 v[4:7], v74 offset:28160
	ds_read_b128 v[12:15], v75 offset:27648
	v_add_f32_dpp v20, v20, v20 row_half_mirror row_mask:0xf bank_mask:0xf bound_ctrl:1
	ds_read_b128 v[8:11], v74 offset:28416
	ds_write_b32 v72, v21 offset:3072
	v_add_f32_dpp v20, v20, v20 row_mirror row_mask:0xf bank_mask:0xf bound_ctrl:1
	v_pk_fma_f32 v[58:59], v[28:29], v[20:21], v[32:33] op_sel_hi:[1,0,1]
	v_pk_fma_f32 v[60:61], v[30:31], v[20:21], v[34:35] op_sel_hi:[1,0,1]
	s_waitcnt lgkmcnt(7)
	v_pk_mul_f32 v[46:47], v[58:59], v[46:47] op_sel_hi:[0,1]
	v_pk_fma_f32 v[46:47], v[58:59], v[48:49], v[46:47] op_sel:[1,0,0] op_sel_hi:[1,1,1]
	v_pk_fma_f32 v[46:47], v[60:61], v[76:77], v[46:47] op_sel_hi:[0,1,1]
	v_pk_fma_f32 v[46:47], v[60:61], v[78:79], v[46:47] op_sel:[1,0,0] op_sel_hi:[1,1,1]
	v_pk_fma_f32 v[68:69], v[58:59], v[50:51], v[68:69]
	v_pk_fma_f32 v[70:71], v[60:61], v[52:53], v[70:71]
	v_add_f32_dpp v46, v46, v46 quad_perm:[1,0,3,2] row_mask:0xf bank_mask:0xf bound_ctrl:1
	ds_read_b128 v[20:23], v73 offset:30720
	ds_read_b128 v[36:39], v73 offset:30736
	v_add_f32_dpp v46, v46, v46 quad_perm:[2,3,0,1] row_mask:0xf bank_mask:0xf bound_ctrl:1
	ds_read_b128 v[24:27], v74 offset:31232
	ds_read_b128 v[32:35], v75 offset:30720
	v_add_f32_dpp v46, v46, v46 row_half_mirror row_mask:0xf bank_mask:0xf bound_ctrl:1
	ds_read_b128 v[28:31], v74 offset:31488
	ds_write_b32 v72, v47 offset:3584
	v_add_f32_dpp v46, v46, v46 row_mirror row_mask:0xf bank_mask:0xf bound_ctrl:1
	v_pk_fma_f32 v[58:59], v[54:55], v[46:47], v[68:69] op_sel_hi:[1,0,1]
	v_pk_fma_f32 v[60:61], v[56:57], v[46:47], v[70:71] op_sel_hi:[1,0,1]
	s_waitcnt lgkmcnt(7)
; #define LAS __attribute__((address_space(3)))
; #define RW_LDS_WAIT(X) asm volatile("s_waitcnt lgkmcnt(0)" : "+v"(nk##X), "+v"(dd##X), "+v"(bb##X), "+v"(kp##X), "+v"(rr##X), "+v"(vv##X) :: "memory")
; DI void rwkv_scan_phase(int wv, const Params& P, LAS unsigned char* lds) {
;     ...
;                 f32x2 yacc = (f32x2){0.f, 0.f};
;                 unsigned sbt = sba, vbt = vba; LAS float* ybt = yb;
;                 RW_LDS_LOAD(A, 0); RW_LDS_WAIT(A);
; #pragma unroll 1
;                 for (int tt = 0; tt < RW_T; tt += 16) { sbt = sba + (unsigned)tt * 1280u; vbt = vba + (unsigned)tt * 32u; ybt = yb + tt * 128;
;                     RW_LDS_LOAD(B, 1); RW_STEP(A, 0); RW_LDS_WAIT(B);
;                     RW_LDS_LOAD(A, 2); RW_STEP(B, 1); RW_LDS_WAIT(A);
;                     RW_LDS_LOAD(B, 3); RW_STEP(A, 2); RW_LDS_WAIT(B);
;                     RW_LDS_LOAD(A, 4); RW_STEP(B, 3); RW_LDS_WAIT(A);
;                     RW_LDS_LOAD(B, 5); RW_STEP(A, 4); RW_LDS_WAIT(B);
;                     RW_LDS_LOAD(A, 6); RW_STEP(B, 5); RW_LDS_WAIT(A);
;                     RW_LDS_LOAD(B, 7); RW_STEP(A, 6); RW_LDS_WAIT(B);
;                     RW_LDS_LOAD(A, 8); RW_STEP(B, 7); RW_LDS_WAIT(A);
;                     RW_LDS_LOAD(B, 9); RW_STEP(A, 8); RW_LDS_WAIT(B);
;                     RW_LDS_LOAD(A, 10); RW_STEP(B, 9); RW_LDS_WAIT(A);
;                     RW_LDS_LOAD(B, 11); RW_STEP(A, 10); RW_LDS_WAIT(B);
;                     RW_LDS_LOAD(A, 12); RW_STEP(B, 11); RW_LDS_WAIT(A);
;                     RW_LDS_LOAD(B, 13); RW_STEP(A, 12); RW_LDS_WAIT(B);
;                     RW_LDS_LOAD(A, 14); RW_STEP(B, 13); RW_LDS_WAIT(A);
;                     RW_LDS_LOAD(B, 15); RW_STEP(A, 14); RW_LDS_WAIT(B);
;                     RW_LDS_LOAD(A, 16); RW_STEP(B, 15); RW_LDS_WAIT(A);
;                 }
;                 yb[(RW_T - 1) * 128] = yacc[0] + yacc[1];
	v_pk_mul_f32 v[0:1], v[58:59], v[0:1] op_sel_hi:[0,1]
	v_pk_fma_f32 v[0:1], v[58:59], v[2:3], v[0:1] op_sel:[1,0,0] op_sel_hi:[1,1,1]
	v_pk_fma_f32 v[0:1], v[60:61], v[16:17], v[0:1] op_sel_hi:[0,1,1]
	v_pk_fma_f32 v[0:1], v[60:61], v[18:19], v[0:1] op_sel:[1,0,0] op_sel_hi:[1,1,1]
	v_pk_fma_f32 v[12:13], v[58:59], v[4:5], v[12:13]
	v_pk_fma_f32 v[14:15], v[60:61], v[6:7], v[14:15]
	v_add_f32_dpp v0, v0, v0 quad_perm:[1,0,3,2] row_mask:0xf bank_mask:0xf bound_ctrl:1
	ds_read_b128 v[46:49], v73 offset:33792
	ds_read_b128 v[76:79], v73 offset:33808
	v_add_f32_dpp v0, v0, v0 quad_perm:[2,3,0,1] row_mask:0xf bank_mask:0xf bound_ctrl:1
	ds_read_b128 v[50:53], v74 offset:34304
	ds_read_b128 v[68:71], v75 offset:33792
	v_add_f32_dpp v0, v0, v0 row_half_mirror row_mask:0xf bank_mask:0xf bound_ctrl:1
	ds_read_b128 v[54:57], v74 offset:34560
	ds_write_b32 v72, v1 offset:4096
	v_add_f32_dpp v0, v0, v0 row_mirror row_mask:0xf bank_mask:0xf bound_ctrl:1
	v_pk_fma_f32 v[58:59], v[8:9], v[0:1], v[12:13] op_sel_hi:[1,0,1]
	v_pk_fma_f32 v[60:61], v[10:11], v[0:1], v[14:15] op_sel_hi:[1,0,1]
	s_waitcnt lgkmcnt(7)
	v_pk_mul_f32 v[20:21], v[58:59], v[20:21] op_sel_hi:[0,1]
	v_pk_fma_f32 v[20:21], v[58:59], v[22:23], v[20:21] op_sel:[1,0,0] op_sel_hi:[1,1,1]
	v_pk_fma_f32 v[20:21], v[60:61], v[36:37], v[20:21] op_sel_hi:[0,1,1]
	v_pk_fma_f32 v[20:21], v[60:61], v[38:39], v[20:21] op_sel:[1,0,0] op_sel_hi:[1,1,1]
	v_pk_fma_f32 v[32:33], v[58:59], v[24:25], v[32:33]
	v_pk_fma_f32 v[34:35], v[60:61], v[26:27], v[34:35]
	v_add_f32_dpp v20, v20, v20 quad_perm:[1,0,3,2] row_mask:0xf bank_mask:0xf bound_ctrl:1
	ds_read_b128 v[0:3], v73 offset:36864
	ds_read_b128 v[16:19], v73 offset:36880
	v_add_f32_dpp v20, v20, v20 quad_perm:[2,3,0,1] row_mask:0xf bank_mask:0xf bound_ctrl:1
	ds_read_b128 v[4:7], v74 offset:37376
	ds_read_b128 v[12:15], v75 offset:36864
	v_add_f32_dpp v20, v20, v20 row_half_mirror row_mask:0xf bank_mask:0xf bound_ctrl:1
	ds_read_b128 v[8:11], v74 offset:37632
	ds_write_b32 v72, v21 offset:4608
	v_add_f32_dpp v20, v20, v20 row_mirror row_mask:0xf bank_mask:0xf bound_ctrl:1
	v_pk_fma_f32 v[58:59], v[28:29], v[20:21], v[32:33] op_sel_hi:[1,0,1]
	v_pk_fma_f32 v[60:61], v[30:31], v[20:21], v[34:35] op_sel_hi:[1,0,1]
	s_waitcnt lgkmcnt(7)
	v_pk_mul_f32 v[46:47], v[58:59], v[46:47] op_sel_hi:[0,1]
	v_pk_fma_f32 v[46:47], v[58:59], v[48:49], v[46:47] op_sel:[1,0,0] op_sel_hi:[1,1,1]
	v_pk_fma_f32 v[46:47], v[60:61], v[76:77], v[46:47] op_sel_hi:[0,1,1]
	v_pk_fma_f32 v[46:47], v[60:61], v[78:79], v[46:47] op_sel:[1,0,0] op_sel_hi:[1,1,1]
	v_pk_fma_f32 v[68:69], v[58:59], v[50:51], v[68:69]
	v_pk_fma_f32 v[70:71], v[60:61], v[52:53], v[70:71]
	v_add_f32_dpp v46, v46, v46 quad_perm:[1,0,3,2] row_mask:0xf bank_mask:0xf bound_ctrl:1
	ds_read_b128 v[20:23], v73 offset:39936
	ds_read_b128 v[36:39], v73 offset:39952
	v_add_f32_dpp v46, v46, v46 quad_perm:[2,3,0,1] row_mask:0xf bank_mask:0xf bound_ctrl:1
	ds_read_b128 v[24:27], v74 offset:40448
	ds_read_b128 v[32:35], v75 offset:39936
	v_add_f32_dpp v46, v46, v46 row_half_mirror row_mask:0xf bank_mask:0xf bound_ctrl:1
	ds_read_b128 v[28:31], v74 offset:40704
	ds_write_b32 v72, v47 offset:5120
	v_add_f32_dpp v46, v46, v46 row_mirror row_mask:0xf bank_mask:0xf bound_ctrl:1
	v_pk_fma_f32 v[58:59], v[54:55], v[46:47], v[68:69] op_sel_hi:[1,0,1]
	v_pk_fma_f32 v[60:61], v[56:57], v[46:47], v[70:71] op_sel_hi:[1,0,1]
	s_waitcnt lgkmcnt(7)
	v_pk_mul_f32 v[0:1], v[58:59], v[0:1] op_sel_hi:[0,1]
	v_pk_fma_f32 v[0:1], v[58:59], v[2:3], v[0:1] op_sel:[1,0,0] op_sel_hi:[1,1,1]
	v_pk_fma_f32 v[0:1], v[60:61], v[16:17], v[0:1] op_sel_hi:[0,1,1]
	v_pk_fma_f32 v[0:1], v[60:61], v[18:19], v[0:1] op_sel:[1,0,0] op_sel_hi:[1,1,1]
	v_pk_fma_f32 v[12:13], v[58:59], v[4:5], v[12:13]
	v_pk_fma_f32 v[14:15], v[60:61], v[6:7], v[14:15]
	v_add_f32_dpp v0, v0, v0 quad_perm:[1,0,3,2] row_mask:0xf bank_mask:0xf bound_ctrl:1
	ds_read_b128 v[46:49], v73 offset:43008
	ds_read_b128 v[76:79], v73 offset:43024
	v_add_f32_dpp v0, v0, v0 quad_perm:[2,3,0,1] row_mask:0xf bank_mask:0xf bound_ctrl:1
	ds_read_b128 v[50:53], v74 offset:43520
	ds_read_b128 v[68:71], v75 offset:43008
	v_add_f32_dpp v0, v0, v0 row_half_mirror row_mask:0xf bank_mask:0xf bound_ctrl:1
	ds_read_b128 v[54:57], v74 offset:43776
	ds_write_b32 v72, v1 offset:5632
	v_add_f32_dpp v0, v0, v0 row_mirror row_mask:0xf bank_mask:0xf bound_ctrl:1
	v_pk_fma_f32 v[58:59], v[8:9], v[0:1], v[12:13] op_sel_hi:[1,0,1]
	v_pk_fma_f32 v[60:61], v[10:11], v[0:1], v[14:15] op_sel_hi:[1,0,1]
	s_waitcnt lgkmcnt(7)
	v_pk_mul_f32 v[20:21], v[58:59], v[20:21] op_sel_hi:[0,1]
	v_pk_fma_f32 v[20:21], v[58:59], v[22:23], v[20:21] op_sel:[1,0,0] op_sel_hi:[1,1,1]
	v_pk_fma_f32 v[20:21], v[60:61], v[36:37], v[20:21] op_sel_hi:[0,1,1]
	v_pk_fma_f32 v[20:21], v[60:61], v[38:39], v[20:21] op_sel:[1,0,0] op_sel_hi:[1,1,1]
	v_pk_fma_f32 v[32:33], v[58:59], v[24:25], v[32:33]
	v_pk_fma_f32 v[34:35], v[60:61], v[26:27], v[34:35]
	v_add_f32_dpp v20, v20, v20 quad_perm:[1,0,3,2] row_mask:0xf bank_mask:0xf bound_ctrl:1
	ds_read_b128 v[0:3], v73 offset:46080
	ds_read_b128 v[16:19], v73 offset:46096
	v_add_f32_dpp v20, v20, v20 quad_perm:[2,3,0,1] row_mask:0xf bank_mask:0xf bound_ctrl:1
	ds_read_b128 v[4:7], v74 offset:46592
	ds_read_b128 v[12:15], v75 offset:46080
	v_add_f32_dpp v20, v20, v20 row_half_mirror row_mask:0xf bank_mask:0xf bound_ctrl:1
	ds_read_b128 v[8:11], v74 offset:46848
	ds_write_b32 v72, v21 offset:6144
	v_add_f32_dpp v20, v20, v20 row_mirror row_mask:0xf bank_mask:0xf bound_ctrl:1
	v_pk_fma_f32 v[58:59], v[28:29], v[20:21], v[32:33] op_sel_hi:[1,0,1]
	v_pk_fma_f32 v[60:61], v[30:31], v[20:21], v[34:35] op_sel_hi:[1,0,1]
	s_waitcnt lgkmcnt(7)
	v_pk_mul_f32 v[46:47], v[58:59], v[46:47] op_sel_hi:[0,1]
	v_pk_fma_f32 v[46:47], v[58:59], v[48:49], v[46:47] op_sel:[1,0,0] op_sel_hi:[1,1,1]
	v_pk_fma_f32 v[46:47], v[60:61], v[76:77], v[46:47] op_sel_hi:[0,1,1]
	v_pk_fma_f32 v[46:47], v[60:61], v[78:79], v[46:47] op_sel:[1,0,0] op_sel_hi:[1,1,1]
	v_pk_fma_f32 v[68:69], v[58:59], v[50:51], v[68:69]
	v_pk_fma_f32 v[70:71], v[60:61], v[52:53], v[70:71]
	v_add_f32_dpp v46, v46, v46 quad_perm:[1,0,3,2] row_mask:0xf bank_mask:0xf bound_ctrl:1
	ds_read_b128 v[20:23], v40
	ds_write_b32 v72, v47 offset:6656
	v_add_f32_dpp v46, v46, v46 quad_perm:[2,3,0,1] row_mask:0xf bank_mask:0xf bound_ctrl:1
	s_add_i32 s47, s47, 1
	s_add_i32 s42, s42, 0x2000
	v_add_f32_dpp v46, v46, v46 row_half_mirror row_mask:0xf bank_mask:0xf bound_ctrl:1
	s_cmp_eq_u32 s42, 0x6000
	s_cselect_b32 s42, 0, s42
	v_add_f32_dpp v46, v46, v46 row_mirror row_mask:0xf bank_mask:0xf bound_ctrl:1
	v_pk_fma_f32 v[58:59], v[54:55], v[46:47], v[68:69] op_sel_hi:[1,0,1]
	v_pk_fma_f32 v[60:61], v[56:57], v[46:47], v[70:71] op_sel_hi:[1,0,1]
	s_waitcnt lgkmcnt(0)
	s_barrier
; #define LAS __attribute__((address_space(3)))
; #define RW_LDS_WAIT(X) asm volatile("s_waitcnt lgkmcnt(0)" : "+v"(nk##X), "+v"(dd##X), "+v"(bb##X), "+v"(kp##X), "+v"(rr##X), "+v"(vv##X) :: "memory")
; DI void rwkv_scan_phase(int wv, const Params& P, LAS unsigned char* lds) {
;     ...
;                 f32x2 yacc = (f32x2){0.f, 0.f};
;                 unsigned sbt = sba, vbt = vba; LAS float* ybt = yb;
;                 RW_LDS_LOAD(A, 0); RW_LDS_WAIT(A);
; #pragma unroll 1
;                 for (int tt = 0; tt < RW_T; tt += 16) { sbt = sba + (unsigned)tt * 1280u; vbt = vba + (unsigned)tt * 32u; ybt = yb + tt * 128;
;                     RW_LDS_LOAD(B, 1); RW_STEP(A, 0); RW_LDS_WAIT(B);
;                     RW_LDS_LOAD(A, 2); RW_STEP(B, 1); RW_LDS_WAIT(A);
;                     RW_LDS_LOAD(B, 3); RW_STEP(A, 2); RW_LDS_WAIT(B);
;                     RW_LDS_LOAD(A, 4); RW_STEP(B, 3); RW_LDS_WAIT(A);
;                     RW_LDS_LOAD(B, 5); RW_STEP(A, 4); RW_LDS_WAIT(B);
;                     RW_LDS_LOAD(A, 6); RW_STEP(B, 5); RW_LDS_WAIT(A);
;                     RW_LDS_LOAD(B, 7); RW_STEP(A, 6); RW_LDS_WAIT(B);
;                     RW_LDS_LOAD(A, 8); RW_STEP(B, 7); RW_LDS_WAIT(A);
;                     RW_LDS_LOAD(B, 9); RW_STEP(A, 8); RW_LDS_WAIT(B);
;                     RW_LDS_LOAD(A, 10); RW_STEP(B, 9); RW_LDS_WAIT(A);
;                     RW_LDS_LOAD(B, 11); RW_STEP(A, 10); RW_LDS_WAIT(B);
;                     RW_LDS_LOAD(A, 12); RW_STEP(B, 11); RW_LDS_WAIT(A);
;                     RW_LDS_LOAD(B, 13); RW_STEP(A, 12); RW_LDS_WAIT(B);
;                     RW_LDS_LOAD(A, 14); RW_STEP(B, 13); RW_LDS_WAIT(A);
;                     RW_LDS_LOAD(B, 15); RW_STEP(A, 14); RW_LDS_WAIT(B);
;                     RW_LDS_LOAD(A, 16); RW_STEP(B, 15); RW_LDS_WAIT(A);
;                 }
;                 yb[(RW_T - 1) * 128] = yacc[0] + yacc[1];
	v_pk_mul_f32 v[0:1], v[58:59], v[0:1] op_sel_hi:[0,1]
	v_pk_fma_f32 v[0:1], v[58:59], v[2:3], v[0:1] op_sel:[1,0,0] op_sel_hi:[1,1,1]
	v_pk_fma_f32 v[0:1], v[60:61], v[16:17], v[0:1] op_sel_hi:[0,1,1]
	v_pk_fma_f32 v[0:1], v[60:61], v[18:19], v[0:1] op_sel:[1,0,0] op_sel_hi:[1,1,1]
	v_pk_fma_f32 v[12:13], v[58:59], v[4:5], v[12:13]
	v_pk_fma_f32 v[14:15], v[60:61], v[6:7], v[14:15]
	v_add_f32_dpp v0, v0, v0 quad_perm:[1,0,3,2] row_mask:0xf bank_mask:0xf bound_ctrl:1
	ds_write_b32 v72, v1 offset:7168
	s_lshl_b32 s40, s47, 4
	v_add_f32_dpp v0, v0, v0 quad_perm:[2,3,0,1] row_mask:0xf bank_mask:0xf bound_ctrl:1
	s_and_b32 s40, s40, 16
	s_mul_i32 s41, s40, 0xc00
	v_add_f32_dpp v0, v0, v0 row_half_mirror row_mask:0xf bank_mask:0xf bound_ctrl:1
	v_add_u32_e32 v74, s41, v45
	v_add_u32_e32 v73, v74, v45
	v_add_f32_dpp v0, v0, v0 row_mirror row_mask:0xf bank_mask:0xf bound_ctrl:1
	v_pk_fma_f32 v[58:59], v[8:9], v[0:1], v[12:13] op_sel_hi:[1,0,1]
	v_pk_fma_f32 v[60:61], v[10:11], v[0:1], v[14:15] op_sel_hi:[1,0,1]
	v_add_u32_e32 v75, s41, v42
	v_add_u32_e32 v67, s42, v62
	s_lshl_b32 s41, s40, 4
	s_add_i32 s41, s41, 0x1e000
	v_add_u32_e32 v40, s41, v45
	v_pk_mul_f32 v[64:65], v[20:21], v[58:59]
	ds_read_b128 v[0:3], v73
	v_pk_fma_f32 v[64:65], v[22:23], v[60:61], v[64:65]
	ds_read_b128 v[16:19], v73 offset:16
	s_cmpk_eq_i32 s47, 0x200
	v_add_f32_e32 v64, v64, v65
	ds_read_b128 v[4:7], v74 offset:512
	ds_write_b32 v72, v64 offset:7680
	v_mov_b32_e32 v72, v67
	ds_read_b128 v[12:15], v75
	ds_read_b128 v[8:11], v74 offset:768
	ds_read_b128 v[20:23], v73 offset:3072
	ds_read_b128 v[36:39], v73 offset:3088
	ds_read_b128 v[24:27], v74 offset:3584
	ds_read_b128 v[32:35], v75 offset:3072
	ds_read_b128 v[28:31], v74 offset:3840
	s_cbranch_scc0 .Lscan_chunk
	s_waitcnt lgkmcnt(0)
	s_barrier

; #define LAS __attribute__((address_space(3)))
; DI unsigned pk2(float lo, float hi) { f32x2 v = {lo, hi}; bf16x2_t b = __builtin_convertvector(v, bf16x2_t); return __builtin_bit_cast(unsigned, b); }
; DI float row16_sum(float v) { v += dpp_f<0xB1>(v); v += dpp_f<0x4E>(v); v += dpp_f<0x141>(v); v += dpp_f<0x140>(v); return v; }
; DI void rwkv_scan_phase(int wv, const Params& P, LAS unsigned char* lds) {
;     ...
;             const int ch = h * 64 + lane;
;             const float kkw = P.in[35][ch], kaw = P.in[36][ch], rkw = P.in[37][ch];
;             const int hf = lane >> 5, c2 = lane & 31, chp = h * 64 + 2 * c2;
;             const f32x2 kkw2 = *(const f32x2*)(P.in[35] + chp), kaw2 = *(const f32x2*)(P.in[36] + chp), rkw2 = *(const f32x2*)(P.in[37] + chp);
;             unsigned gk[3], ga[3], gr[3], gl[3]; float gv[3];
;     ...
;             RW_LOADG(0)
; #pragma unroll 1
;             for (int ck = -1; ck <= nck; ++ck) {
;                 {
;                     if (ck >= 1) { const LAS float* yb = ybuf + ((ck - 1) & 1) * RW_T * 128;
; #pragma unroll 2
;                         for (int it = pw; it < 64; it += 6) { const float y = row16_sum(yb[it * 64 + lane]);
;                             const float y0 = __builtin_bit_cast(float, __builtin_amdgcn_readlane(__builtin_bit_cast(int, y), 0)), y1 = __builtin_bit_cast(float, __builtin_amdgcn_readlane(__builtin_bit_cast(int, y), 16)),
;                                         y2 = __builtin_bit_cast(float, __builtin_amdgcn_readlane(__builtin_bit_cast(int, y), 32)), y3 = __builtin_bit_cast(float, __builtin_amdgcn_readlane(__builtin_bit_cast(int, y), 48));
;                             if (lane == 0) { u32x2 w; w.x = pk2(y0, y1); w.y = pk2(y2, y3); *(u32x2*)(YS + ((size_t)b * SEQ + (ck - 1) * RW_T + (it >> 1)) * 1024 + h * 64 + rg * 8 + (it & 1) * 4) = w; } } }
;                     if (ck + 1 < nck) { const int cn = ck + 1, buf = cn & 1;
; #pragma unroll
;                         for (int i = 0; i < 3; ++i) { const int pp = pw + 6 * i; if (pp < 16) { const int tt = 2 * pp + hf; const size_t row = (size_t)b * SEQ + cn * RW_T + tt;
.LBB0_3185:
	s_andn2_saveexec_b64 s[40:41], s[20:21]
	s_cbranch_execz .LBB0_3174
	v_readfirstlane_b32 s55, v41
	s_and_b32 s66, s55, 2
	s_cmp_lg_u32 s66, 0
	s_cbranch_scc1 .Lprod_flusher
	s_lshr_b32 s66, s55, 1
	s_and_b32 s55, s55, 1
	s_or_b32 s55, s55, s66
	s_and_b32 s67, s46, 7
	s_bfe_u32 s59, s46, 0x40003
	s_lshr_b32 s60, s46, 7
	s_lshl_b32 s60, s60, 13
	s_lshl_b32 s66, s55, 2
	s_add_i32 s60, s60, s66
	v_mbcnt_lo_u32_b32 v0, -1, 0
	v_mbcnt_hi_u32_b32 v0, -1, v0
	v_and_b32_e32 v1, 31, v0
	v_lshrrev_b32_e32 v31, 5, v0
	s_lshl_b32 s61, s59, 6
	v_lshl_add_u32 v32, v1, 1, s61
	v_lshlrev_b32_e32 v33, 2, v32
	global_load_dwordx2 v[4:5], v33, s[24:25]
	global_load_dwordx2 v[6:7], v33, s[26:27]
	global_load_dwordx2 v[8:9], v33, s[38:39]
	v_add_u32_e32 v34, s60, v31
	v_lshlrev_b32_e32 v35, 11, v34
	v_lshl_add_u32 v12, v32, 1, v35
	v_add_u32_e32 v13, 0x1000, v12
	s_lshl_b32 s66, s55, 2
	v_add_u32_e32 v37, s66, v31
	v_mul_u32_u24_e32 v2, 0xc00, v37
	v_lshl_add_u32 v2, v1, 3, v2
	s_lshl_b32 s66, s59, 2
	v_lshl_add_u32 v10, v34, 6, s66
	v_or_b32_e32 v38, s67, v1
	v_cmp_eq_u32_e64 s[42:43], 0, v38
	s_mov_b32 s57, -1
	s_mov_b32 s67, 0
	s_waitcnt vmcnt(0)
	s_add_u32 s60, s28, s67
	s_addc_u32 s61, s29, 0
	global_load_dword v44, v12, s[60:61]
	global_load_dword v48, v13, s[60:61]
	s_add_u32 s60, s34, s67
	s_addc_u32 s61, s35, 0
	global_load_dword v45, v12, s[60:61]
	global_load_dword v49, v13, s[60:61]
	s_add_u32 s60, s22, s67
	s_addc_u32 s61, s23, 0
	global_load_dword v46, v12, s[60:61]
	global_load_dword v50, v13, s[60:61]
	s_add_u32 s60, s36, s67
	s_addc_u32 s61, s37, 0
	global_load_dword v47, v12, s[60:61]
	global_load_dword v51, v13, s[60:61]
	s_add_u32 s60, s22, s67
	s_addc_u32 s61, s23, 0
	s_sub_u32 s60, s60, 0x800
	s_subb_u32 s61, s61, 0
	global_load_dword v0, v12, s[60:61]
	global_load_dword v40, v13, s[60:61]
	s_mov_b32 s67, 0x8000
	s_add_u32 s60, s28, s67
	s_addc_u32 s61, s29, 0
	global_load_dword v24, v12, s[60:61]
	global_load_dword v28, v13, s[60:61]
	s_add_u32 s60, s34, s67
	s_addc_u32 s61, s35, 0
	global_load_dword v25, v12, s[60:61]
	global_load_dword v29, v13, s[60:61]
	s_add_u32 s60, s22, s67
	s_addc_u32 s61, s23, 0
	global_load_dword v26, v12, s[60:61]
	global_load_dword v30, v13, s[60:61]
	s_add_u32 s60, s36, s67
	s_addc_u32 s61, s37, 0
	global_load_dword v27, v12, s[60:61]
	global_load_dword v31, v13, s[60:61]
	s_add_u32 s60, s22, s67
	s_addc_u32 s61, s23, 0
	s_sub_u32 s60, s60, 0x800
	s_subb_u32 s61, s61, 0
	global_load_dword v3, v12, s[60:61]
	global_load_dword v43, v13, s[60:61]
.Lprod_loop:
.Lprod_half_0:
	s_cmp_gt_i32 s57, 0x1fe
	s_cbranch_scc1 .Lprod_sync_0
	s_add_i32 s67, s57, 1
	v_mov_b32_e32 v22, v2
	v_lshl_add_u32 v21, v1, 3, v22
	v_mov_b32_e32 v23, 0x1e000
	v_lshl_add_u32 v23, v1, 3, v23
	s_lshl_b32 s60, s67, 10
	s_add_u32 s62, s50, s60
	s_addc_u32 s63, s51, 0
	s_cmp_gt_i32 s57, 0x1fd
	s_cbranch_scc1 .Lprod_w0_0
	s_waitcnt vmcnt(10)
	s_branch .Lprod_wd_0

; #define LAS __attribute__((address_space(3)))
; DI float bflo(unsigned u) { return __uint_as_float(u << 16); }
; DI float bfhi(unsigned u) { return __uint_as_float(u & 0xffff0000u); }
; template <int CTRL> DI float dpp_f(float v) { return __builtin_bit_cast(float, __builtin_amdgcn_update_dpp(0, __builtin_bit_cast(int, v), CTRL, 0xf, 0xf, true)); }
; DI void rwkv_scan_phase(int wv, const Params& P, LAS unsigned char* lds) {
;     ...
;                         for (int i = 0; i < 3; ++i) { const int pp = pw + 6 * i; if (pp < 16) { const int tt = 2 * pp + hf; const size_t row = (size_t)b * SEQ + cn * RW_T + tt;
;                             const f32x2 k = {bflo(gk[i]), bfhi(gk[i])}, a = {bflo(ga[i]), bfhi(ga[i])}, r = {bflo(gr[i]), bfhi(gr[i])};
;                             const h16x2 lh = __builtin_bit_cast(h16x2, gl[i]);
;                             const f32x2 kr = k * kkw2, kp = k * ((a - 1.f) * kaw2 + 1.f);
;                             const float sp = kr[0] * kr[0] + kr[1] * kr[1], rp = r[0] * kp[0] * rkw2[0] + r[1] * kp[1] * rkw2[1];
;                             const bool odd = lane & 1;
;                             float red = (odd ? rp : sp) + dpp_f<0xB1>(odd ? sp : rp);
;                             red += dpp_f<0x4E>(red); red += dpp_f<0x124>(red); red += dpp_f<0x128>(red);
;                             { auto x = __builtin_amdgcn_permlane16_swap(__float_as_uint(red), __float_as_uint(red), false, false); red = __uint_as_float(x[0]) + __uint_as_float(x[1]); }
;                             const float oth = dpp_f<0xB1>(red); const float ss = odd ? oth : red, rks = odd ? red : oth;
;                             const f32x2 kk = kr * __builtin_amdgcn_rsqf(fmaxf(ss, 1e-24f));
;                             LAS float* d = stg + ((buf * RW_T + tt) * 5) * 64 + 2 * c2;
;                             *(LAS f32x2*)(d) = -kk; *(LAS f32x2*)(d + 64) = (f32x2){__expf((float)lh[0]), __expf((float)lh[1])}; *(LAS f32x2*)(d + 128) = kk * a; *(LAS f32x2*)(d + 192) = kp; *(LAS f32x2*)(d + 256) = r;
;                             if (rg == 0 && c2 == 0) RK[row * 16 + h] = rks;
;                             if (c2 < 8) vst[(buf * RW_T + tt) * 8 + c2] = gv[i]; } }
;                         if (ck + 2 < nck) { RW_LOADG(ck + 2) } }
.Lprod_wd_0:
	v_lshlrev_b32_e32 v64, 16, v45
	v_and_b32_e32 v65, 0xffff0000, v45
	v_pk_add_f32 v[72:73], v[64:65], -1.0 op_sel_hi:[1,0]
	v_lshlrev_b32_e32 v66, 16, v44
	v_and_b32_e32 v67, 0xffff0000, v44
	v_pk_fma_f32 v[72:73], v[6:7], v[72:73], 1.0 op_sel_hi:[1,1,0]
	v_and_b32_e32 v69, 0xffff0000, v46
	v_pk_mul_f32 v[70:71], v[4:5], v[66:67]
	v_pk_mul_f32 v[66:67], v[72:73], v[66:67]
	v_lshlrev_b32_e32 v68, 16, v46
	v_mul_f32_e32 v75, v67, v69
	v_pk_mul_f32 v[72:73], v[70:71], v[70:71]
	v_mul_f32_e32 v74, v66, v68
	v_mul_f32_e32 v75, v9, v75
	v_add_f32_e32 v76, v72, v73
	v_fmac_f32_e32 v75, v8, v74
	v_cndmask_b32_e64 v74, v75, v76, s[8:9]
	v_cndmask_b32_e64 v76, v76, v75, s[8:9]
	v_cvt_f32_f16_e32 v77, v47
	v_cvt_f32_f16_sdwa v78, v47 dst_sel:DWORD dst_unused:UNUSED_PAD src0_sel:WORD_1
	v_add_f32_dpp v76, v76, v74 quad_perm:[1,0,3,2] row_mask:0xf bank_mask:0xf bound_ctrl:1
	v_mul_f32_e32 v77, 0x3fb8aa3b, v77
	s_nop 0
	v_add_f32_dpp v76, v76, v76 quad_perm:[2,3,0,1] row_mask:0xf bank_mask:0xf bound_ctrl:1
	v_exp_f32_e32 v72, v77
	v_mul_f32_e32 v77, 0x3fb8aa3b, v78
	v_add_f32_dpp v76, v76, v76 row_ror:4 row_mask:0xf bank_mask:0xf bound_ctrl:1
	v_exp_f32_e32 v73, v77
	s_nop 0
	v_add_f32_dpp v76, v76, v76 row_ror:8 row_mask:0xf bank_mask:0xf bound_ctrl:1
	v_mov_b32_e32 v74, v76
	s_nop 1
	v_permlane16_swap_b32_e32 v76, v74
	v_add_f32_e32 v76, v76, v74
	s_nop 1
	v_mov_b32_dpp v74, v76 quad_perm:[1,0,3,2] row_mask:0xf bank_mask:0xf bound_ctrl:1
	v_cndmask_b32_e64 v75, v74, v76, s[8:9]
	v_max_f32_e32 v75, v75, v75
	v_max_f32_e32 v75, 0x179abe15, v75
	v_rsq_f32_e32 v42, v75
	v_cndmask_b32_e64 v76, v76, v74, s[8:9]
	s_nop 0
	v_pk_mul_f32 v[70:71], v[70:71], v[42:43] op_sel_hi:[1,0] neg_lo:[0,1] neg_hi:[0,1]
	ds_write_b64 v22, v[72:73] offset:512
	s_nop 0
	v_pk_mul_f32 v[64:65], v[70:71], v[64:65] neg_lo:[1,0] neg_hi:[1,0]
	v_mov_b32_e32 v72, v71
	v_lshlrev_b32_e32 v71, 16, v0
	ds_write_b64 v22, v[64:65] offset:768
	v_and_b32_e32 v73, 0xffff0000, v0
	ds_write_b128 v21, v[70:73]
	s_and_saveexec_b64 s[60:61], s[42:43]
	s_cbranch_execz .Lprod_rk_skip_0_0
	global_store_dword v10, v76, s[62:63]
.Lprod_rk_skip_0_0:
	s_mov_b64 exec, -1
	v_lshlrev_b32_e32 v64, 16, v49
	v_and_b32_e32 v65, 0xffff0000, v49
	v_pk_add_f32 v[72:73], v[64:65], -1.0 op_sel_hi:[1,0]
	v_lshlrev_b32_e32 v66, 16, v48
	v_and_b32_e32 v67, 0xffff0000, v48
	v_pk_fma_f32 v[72:73], v[6:7], v[72:73], 1.0 op_sel_hi:[1,1,0]
	v_and_b32_e32 v69, 0xffff0000, v50
	v_pk_mul_f32 v[70:71], v[4:5], v[66:67]
	v_pk_mul_f32 v[66:67], v[72:73], v[66:67]
	v_lshlrev_b32_e32 v68, 16, v50
	v_mul_f32_e32 v75, v67, v69
	v_pk_mul_f32 v[72:73], v[70:71], v[70:71]
	v_mul_f32_e32 v74, v66, v68
	v_mul_f32_e32 v75, v9, v75
	v_add_f32_e32 v76, v72, v73
	v_fmac_f32_e32 v75, v8, v74
	v_cndmask_b32_e64 v74, v75, v76, s[8:9]
	v_cndmask_b32_e64 v76, v76, v75, s[8:9]
	v_cvt_f32_f16_e32 v77, v51
	v_cvt_f32_f16_sdwa v78, v51 dst_sel:DWORD dst_unused:UNUSED_PAD src0_sel:WORD_1
	v_add_f32_dpp v76, v76, v74 quad_perm:[1,0,3,2] row_mask:0xf bank_mask:0xf bound_ctrl:1
	v_mul_f32_e32 v77, 0x3fb8aa3b, v77
	s_nop 0
	v_add_f32_dpp v76, v76, v76 quad_perm:[2,3,0,1] row_mask:0xf bank_mask:0xf bound_ctrl:1
	v_exp_f32_e32 v72, v77
	v_mul_f32_e32 v77, 0x3fb8aa3b, v78
	v_add_f32_dpp v76, v76, v76 row_ror:4 row_mask:0xf bank_mask:0xf bound_ctrl:1
	v_exp_f32_e32 v73, v77
	s_nop 0
	v_add_f32_dpp v76, v76, v76 row_ror:8 row_mask:0xf bank_mask:0xf bound_ctrl:1
	v_mov_b32_e32 v74, v76
	s_nop 1
	v_permlane16_swap_b32_e32 v76, v74
	v_add_f32_e32 v76, v76, v74
	s_nop 1
	v_mov_b32_dpp v74, v76 quad_perm:[1,0,3,2] row_mask:0xf bank_mask:0xf bound_ctrl:1
	v_cndmask_b32_e64 v75, v74, v76, s[8:9]
	v_max_f32_e32 v75, v75, v75
	v_max_f32_e32 v75, 0x179abe15, v75
	v_rsq_f32_e32 v42, v75
	v_cndmask_b32_e64 v76, v76, v74, s[8:9]
	s_nop 0
	v_pk_mul_f32 v[70:71], v[70:71], v[42:43] op_sel_hi:[1,0] neg_lo:[0,1] neg_hi:[0,1]
	ds_write_b64 v22, v[72:73] offset:6656
	s_nop 0
	v_pk_mul_f32 v[64:65], v[70:71], v[64:65] neg_lo:[1,0] neg_hi:[1,0]
	v_mov_b32_e32 v72, v71
	v_lshlrev_b32_e32 v71, 16, v40
	ds_write_b64 v22, v[64:65] offset:6912
	v_and_b32_e32 v73, 0xffff0000, v40
	ds_write_b128 v21, v[70:73] offset:6144
	s_and_saveexec_b64 s[60:61], s[42:43]
	s_cbranch_execz .Lprod_rk_skip_0_1
	global_store_dword v10, v76, s[62:63] offset:128
.Lprod_rk_skip_0_1:
	s_mov_b64 exec, -1
	s_cmp_lg_u32 s55, 3
	s_cbranch_scc1 .Lprod_no_rl_0
	s_mov_b32 exec_lo, 0
	ds_write_b64 v23, v[68:69]
	s_mov_b64 exec, -1
.Lprod_no_rl_0:
	s_cmp_gt_i32 s57, 0x1fc
	s_cbranch_scc1 .Lprod_sync_0
	s_add_i32 s67, s57, 3
	s_lshl_b32 s67, s67, 15
	s_add_u32 s60, s28, s67
	s_addc_u32 s61, s29, 0
	global_load_dword v44, v12, s[60:61]
	global_load_dword v48, v13, s[60:61]
	s_add_u32 s60, s34, s67
	s_addc_u32 s61, s35, 0
	global_load_dword v45, v12, s[60:61]
	global_load_dword v49, v13, s[60:61]
	s_add_u32 s60, s22, s67
	s_addc_u32 s61, s23, 0
	global_load_dword v46, v12, s[60:61]
	global_load_dword v50, v13, s[60:61]
	s_add_u32 s60, s36, s67
	s_addc_u32 s61, s37, 0
	global_load_dword v47, v12, s[60:61]
	global_load_dword v51, v13, s[60:61]
	s_add_u32 s60, s22, s67
	s_addc_u32 s61, s23, 0
	s_sub_u32 s60, s60, 0x800
	s_subb_u32 s61, s61, 0
	global_load_dword v0, v12, s[60:61]
	global_load_dword v40, v13, s[60:61]
.Lprod_sync_0:
	s_cmpk_eq_i32 s57, 0x201
	s_cbranch_scc1 .Lprod_done
	s_waitcnt lgkmcnt(0)
	s_barrier
	s_add_i32 s57, s57, 1
.Lprod_half_1:
	s_cmp_gt_i32 s57, 0x1fe
	s_cbranch_scc1 .Lprod_sync_1
	s_add_i32 s67, s57, 1
	v_add_u32_e32 v22, 0xc000, v2
	v_lshl_add_u32 v21, v1, 3, v22
	v_mov_b32_e32 v23, 0x1e100
	v_lshl_add_u32 v23, v1, 3, v23
	s_lshl_b32 s60, s67, 10
	s_add_u32 s62, s50, s60
	s_addc_u32 s63, s51, 0
	s_cmp_gt_i32 s57, 0x1fd
	s_cbranch_scc1 .Lprod_w0_1
	s_waitcnt vmcnt(10)
	s_branch .Lprod_wd_1

; #define LAS __attribute__((address_space(3)))
; DI float bflo(unsigned u) { return __uint_as_float(u << 16); }
; DI float bfhi(unsigned u) { return __uint_as_float(u & 0xffff0000u); }
; template <int CTRL> DI float dpp_f(float v) { return __builtin_bit_cast(float, __builtin_amdgcn_update_dpp(0, __builtin_bit_cast(int, v), CTRL, 0xf, 0xf, true)); }
; DI void rwkv_scan_phase(int wv, const Params& P, LAS unsigned char* lds) {
;     ...
;                         for (int i = 0; i < 3; ++i) { const int pp = pw + 6 * i; if (pp < 16) { const int tt = 2 * pp + hf; const size_t row = (size_t)b * SEQ + cn * RW_T + tt;
;                             const f32x2 k = {bflo(gk[i]), bfhi(gk[i])}, a = {bflo(ga[i]), bfhi(ga[i])}, r = {bflo(gr[i]), bfhi(gr[i])};
;                             const h16x2 lh = __builtin_bit_cast(h16x2, gl[i]);
;                             const f32x2 kr = k * kkw2, kp = k * ((a - 1.f) * kaw2 + 1.f);
;                             const float sp = kr[0] * kr[0] + kr[1] * kr[1], rp = r[0] * kp[0] * rkw2[0] + r[1] * kp[1] * rkw2[1];
;                             const bool odd = lane & 1;
;                             float red = (odd ? rp : sp) + dpp_f<0xB1>(odd ? sp : rp);
;                             red += dpp_f<0x4E>(red); red += dpp_f<0x124>(red); red += dpp_f<0x128>(red);
;                             { auto x = __builtin_amdgcn_permlane16_swap(__float_as_uint(red), __float_as_uint(red), false, false); red = __uint_as_float(x[0]) + __uint_as_float(x[1]); }
;                             const float oth = dpp_f<0xB1>(red); const float ss = odd ? oth : red, rks = odd ? red : oth;
;                             const f32x2 kk = kr * __builtin_amdgcn_rsqf(fmaxf(ss, 1e-24f));
;                             LAS float* d = stg + ((buf * RW_T + tt) * 5) * 64 + 2 * c2;
;                             *(LAS f32x2*)(d) = -kk; *(LAS f32x2*)(d + 64) = (f32x2){__expf((float)lh[0]), __expf((float)lh[1])}; *(LAS f32x2*)(d + 128) = kk * a; *(LAS f32x2*)(d + 192) = kp; *(LAS f32x2*)(d + 256) = r;
;                             if (rg == 0 && c2 == 0) RK[row * 16 + h] = rks;
;                             if (c2 < 8) vst[(buf * RW_T + tt) * 8 + c2] = gv[i]; } }
.Lprod_wd_1:
	v_lshlrev_b32_e32 v64, 16, v25
	v_and_b32_e32 v65, 0xffff0000, v25
	v_pk_add_f32 v[72:73], v[64:65], -1.0 op_sel_hi:[1,0]
	v_lshlrev_b32_e32 v66, 16, v24
	v_and_b32_e32 v67, 0xffff0000, v24
	v_pk_fma_f32 v[72:73], v[6:7], v[72:73], 1.0 op_sel_hi:[1,1,0]
	v_and_b32_e32 v69, 0xffff0000, v26
	v_pk_mul_f32 v[70:71], v[4:5], v[66:67]
	v_pk_mul_f32 v[66:67], v[72:73], v[66:67]
	v_lshlrev_b32_e32 v68, 16, v26
	v_mul_f32_e32 v75, v67, v69
	v_pk_mul_f32 v[72:73], v[70:71], v[70:71]
	v_mul_f32_e32 v74, v66, v68
	v_mul_f32_e32 v75, v9, v75
	v_add_f32_e32 v76, v72, v73
	v_fmac_f32_e32 v75, v8, v74
	v_cndmask_b32_e64 v74, v75, v76, s[8:9]
	v_cndmask_b32_e64 v76, v76, v75, s[8:9]
	v_cvt_f32_f16_e32 v77, v27
	v_cvt_f32_f16_sdwa v78, v27 dst_sel:DWORD dst_unused:UNUSED_PAD src0_sel:WORD_1
	v_add_f32_dpp v76, v76, v74 quad_perm:[1,0,3,2] row_mask:0xf bank_mask:0xf bound_ctrl:1
	v_mul_f32_e32 v77, 0x3fb8aa3b, v77
	s_nop 0
	v_add_f32_dpp v76, v76, v76 quad_perm:[2,3,0,1] row_mask:0xf bank_mask:0xf bound_ctrl:1
	v_exp_f32_e32 v72, v77
	v_mul_f32_e32 v77, 0x3fb8aa3b, v78
	v_add_f32_dpp v76, v76, v76 row_ror:4 row_mask:0xf bank_mask:0xf bound_ctrl:1
	v_exp_f32_e32 v73, v77
	s_nop 0
	v_add_f32_dpp v76, v76, v76 row_ror:8 row_mask:0xf bank_mask:0xf bound_ctrl:1
	v_mov_b32_e32 v74, v76
	s_nop 1
	v_permlane16_swap_b32_e32 v76, v74
	v_add_f32_e32 v76, v76, v74
	s_nop 1
	v_mov_b32_dpp v74, v76 quad_perm:[1,0,3,2] row_mask:0xf bank_mask:0xf bound_ctrl:1
	v_cndmask_b32_e64 v75, v74, v76, s[8:9]
	v_max_f32_e32 v75, v75, v75
	v_max_f32_e32 v75, 0x179abe15, v75
	v_rsq_f32_e32 v42, v75
	v_cndmask_b32_e64 v76, v76, v74, s[8:9]
	s_nop 0
	v_pk_mul_f32 v[70:71], v[70:71], v[42:43] op_sel_hi:[1,0] neg_lo:[0,1] neg_hi:[0,1]
	ds_write_b64 v22, v[72:73] offset:512
	s_nop 0
	v_pk_mul_f32 v[64:65], v[70:71], v[64:65] neg_lo:[1,0] neg_hi:[1,0]
	v_mov_b32_e32 v72, v71
	v_lshlrev_b32_e32 v71, 16, v3
	ds_write_b64 v22, v[64:65] offset:768
	v_and_b32_e32 v73, 0xffff0000, v3
	ds_write_b128 v21, v[70:73]
	s_and_saveexec_b64 s[60:61], s[42:43]
	s_cbranch_execz .Lprod_rk_skip_1_0
	global_store_dword v10, v76, s[62:63]
.Lprod_rk_skip_1_0:
	s_mov_b64 exec, -1
	v_lshlrev_b32_e32 v64, 16, v29
	v_and_b32_e32 v65, 0xffff0000, v29
	v_pk_add_f32 v[72:73], v[64:65], -1.0 op_sel_hi:[1,0]
	v_lshlrev_b32_e32 v66, 16, v28
	v_and_b32_e32 v67, 0xffff0000, v28
	v_pk_fma_f32 v[72:73], v[6:7], v[72:73], 1.0 op_sel_hi:[1,1,0]
	v_and_b32_e32 v69, 0xffff0000, v30
	v_pk_mul_f32 v[70:71], v[4:5], v[66:67]
	v_pk_mul_f32 v[66:67], v[72:73], v[66:67]
	v_lshlrev_b32_e32 v68, 16, v30
	v_mul_f32_e32 v75, v67, v69
	v_pk_mul_f32 v[72:73], v[70:71], v[70:71]
	v_mul_f32_e32 v74, v66, v68
	v_mul_f32_e32 v75, v9, v75
	v_add_f32_e32 v76, v72, v73
	v_fmac_f32_e32 v75, v8, v74
	v_cndmask_b32_e64 v74, v75, v76, s[8:9]
	v_cndmask_b32_e64 v76, v76, v75, s[8:9]
	v_cvt_f32_f16_e32 v77, v31
	v_cvt_f32_f16_sdwa v78, v31 dst_sel:DWORD dst_unused:UNUSED_PAD src0_sel:WORD_1
	v_add_f32_dpp v76, v76, v74 quad_perm:[1,0,3,2] row_mask:0xf bank_mask:0xf bound_ctrl:1
	v_mul_f32_e32 v77, 0x3fb8aa3b, v77
	s_nop 0
	v_add_f32_dpp v76, v76, v76 quad_perm:[2,3,0,1] row_mask:0xf bank_mask:0xf bound_ctrl:1
	v_exp_f32_e32 v72, v77
	v_mul_f32_e32 v77, 0x3fb8aa3b, v78
	v_add_f32_dpp v76, v76, v76 row_ror:4 row_mask:0xf bank_mask:0xf bound_ctrl:1
	v_exp_f32_e32 v73, v77
	s_nop 0
	v_add_f32_dpp v76, v76, v76 row_ror:8 row_mask:0xf bank_mask:0xf bound_ctrl:1
	v_mov_b32_e32 v74, v76
	s_nop 1
	v_permlane16_swap_b32_e32 v76, v74
	v_add_f32_e32 v76, v76, v74
	s_nop 1
	v_mov_b32_dpp v74, v76 quad_perm:[1,0,3,2] row_mask:0xf bank_mask:0xf bound_ctrl:1
	v_cndmask_b32_e64 v75, v74, v76, s[8:9]
	v_max_f32_e32 v75, v75, v75
	v_max_f32_e32 v75, 0x179abe15, v75
	v_rsq_f32_e32 v42, v75
	v_cndmask_b32_e64 v76, v76, v74, s[8:9]
	s_nop 0
	v_pk_mul_f32 v[70:71], v[70:71], v[42:43] op_sel_hi:[1,0] neg_lo:[0,1] neg_hi:[0,1]
	ds_write_b64 v22, v[72:73] offset:6656
	s_nop 0
	v_pk_mul_f32 v[64:65], v[70:71], v[64:65] neg_lo:[1,0] neg_hi:[1,0]
	v_mov_b32_e32 v72, v71
	v_lshlrev_b32_e32 v71, 16, v43
	ds_write_b64 v22, v[64:65] offset:6912
	v_and_b32_e32 v73, 0xffff0000, v43
	ds_write_b128 v21, v[70:73] offset:6144
	s_and_saveexec_b64 s[60:61], s[42:43]
	s_cbranch_execz .Lprod_rk_skip_1_1
	global_store_dword v10, v76, s[62:63] offset:128

; DI void rwkv_scan_phase(int wv, const Params& P, LAS unsigned char* lds) {
;     ...
;             RW_LOADG(0)
; #pragma unroll 1
;             for (int ck = -1; ck <= nck; ++ck) {
;                 {
;                     if (ck >= 1) { const LAS float* yb = ybuf + ((ck - 1) & 1) * RW_T * 128;
; #pragma unroll 2
;                         for (int it = pw; it < 64; it += 6) { const float y = row16_sum(yb[it * 64 + lane]);
;                             const float y0 = __builtin_bit_cast(float, __builtin_amdgcn_readlane(__builtin_bit_cast(int, y), 0)), y1 = __builtin_bit_cast(float, __builtin_amdgcn_readlane(__builtin_bit_cast(int, y), 16)),
;                                         y2 = __builtin_bit_cast(float, __builtin_amdgcn_readlane(__builtin_bit_cast(int, y), 32)), y3 = __builtin_bit_cast(float, __builtin_amdgcn_readlane(__builtin_bit_cast(int, y), 48));
;                             if (lane == 0) { u32x2 w; w.x = pk2(y0, y1); w.y = pk2(y2, y3); *(u32x2*)(YS + ((size_t)b * SEQ + (ck - 1) * RW_T + (it >> 1)) * 1024 + h * 64 + rg * 8 + (it & 1) * 4) = w; } } }
;                     if (ck + 1 < nck) { const int cn = ck + 1, buf = cn & 1;
; #pragma unroll
;                         for (int i = 0; i < 3; ++i) { const int pp = pw + 6 * i; if (pp < 16) { const int tt = 2 * pp + hf; const size_t row = (size_t)b * SEQ + cn * RW_T + tt;
;                             const f32x2 k = {bflo(gk[i]), bfhi(gk[i])}, a = {bflo(ga[i]), bfhi(ga[i])}, r = {bflo(gr[i]), bfhi(gr[i])};
;                             const h16x2 lh = __builtin_bit_cast(h16x2, gl[i]);
;                             const f32x2 kr = k * kkw2, kp = k * ((a - 1.f) * kaw2 + 1.f);
;                             const float sp = kr[0] * kr[0] + kr[1] * kr[1], rp = r[0] * kp[0] * rkw2[0] + r[1] * kp[1] * rkw2[1];
;                             const bool odd = lane & 1;
;                             float red = (odd ? rp : sp) + dpp_f<0xB1>(odd ? sp : rp);
;                             red += dpp_f<0x4E>(red); red += dpp_f<0x124>(red); red += dpp_f<0x128>(red);
;                             { auto x = __builtin_amdgcn_permlane16_swap(__float_as_uint(red), __float_as_uint(red), false, false); red = __uint_as_float(x[0]) + __uint_as_float(x[1]); }
;                             const float oth = dpp_f<0xB1>(red); const float ss = odd ? oth : red, rks = odd ? red : oth;
.Lprod_no_rl_1:
	s_cmp_gt_i32 s57, 0x1fc
	s_cbranch_scc1 .Lprod_sync_1
	s_add_i32 s67, s57, 3
	s_lshl_b32 s67, s67, 15
	s_add_u32 s60, s28, s67
	s_addc_u32 s61, s29, 0
	global_load_dword v24, v12, s[60:61]
	global_load_dword v28, v13, s[60:61]
	s_add_u32 s60, s34, s67
	s_addc_u32 s61, s35, 0
	global_load_dword v25, v12, s[60:61]
	global_load_dword v29, v13, s[60:61]
	s_add_u32 s60, s22, s67
	s_addc_u32 s61, s23, 0
	global_load_dword v26, v12, s[60:61]
	global_load_dword v30, v13, s[60:61]
	s_add_u32 s60, s36, s67
	s_addc_u32 s61, s37, 0
	global_load_dword v27, v12, s[60:61]
	global_load_dword v31, v13, s[60:61]
	s_add_u32 s60, s22, s67
	s_addc_u32 s61, s23, 0
	s_sub_u32 s60, s60, 0x800
	s_subb_u32 s61, s61, 0
	global_load_dword v3, v12, s[60:61]
	global_load_dword v43, v13, s[60:61]
.Lprod_sync_1:
	s_cmpk_eq_i32 s57, 0x201
	s_cbranch_scc1 .Lprod_done
	s_waitcnt lgkmcnt(0)
	s_barrier
	s_add_i32 s57, s57, 1
	s_branch .Lprod_loop
.Lprod_flusher:
	s_and_b32 s55, s55, 1
	s_and_b32 s67, s46, 7
	s_bfe_u32 s59, s46, 0x40003
	s_lshl_b32 s61, s59, 6
	v_mbcnt_lo_u32_b32 v0, -1, 0
	v_mbcnt_hi_u32_b32 v0, -1, v0
	v_and_b32_e32 v1, 15, v0
	v_lshrrev_b32_e32 v34, 4, v0
	v_lshl_add_u32 v35, v1, 2, s61
	v_lshlrev_b32_e32 v24, 2, v35
	global_load_dwordx4 v[4:7], v24, s[26:27]
	s_lshr_b32 s60, s46, 7
	s_lshl_b32 s60, s60, 13
	s_lshl_b32 s66, s55, 3
	s_add_i32 s60, s60, s66
	v_add_u32_e32 v25, s60, v34
	v_lshlrev_b32_e32 v26, 11, v25
	v_lshl_add_u32 v12, v35, 1, v26
	v_add_u32_e32 v13, 0x2000, v12
	s_lshl_b32 s62, s67, 3
	s_add_i32 s62, s62, s61
	v_mov_b32_e32 v27, s62
	v_lshl_add_u32 v14, v27, 1, v26
	v_add_u32_e32 v15, 0x2000, v14
	v_add_u32_e32 v25, s66, v34
	v_mul_u32_u24_e32 v2, 0xc00, v25
	v_lshl_add_u32 v2, v1, 4, v2
	v_add_u32_e32 v2, 0x400, v2
	v_and_b32_e32 v36, 7, v0
	v_lshrrev_b32_e32 v37, 3, v0
	v_add_u32_e32 v37, s66, v37
	v_lshlrev_b32_e32 v3, 9, v37
	v_lshl_add_u32 v3, v36, 6, v3
	v_add_u32_e32 v3, 0x18000, v3
	s_lshr_b32 s60, s46, 7
	s_lshl_b32 s60, s60, 13
	v_add_u32_e32 v37, s60, v37
	v_lshlrev_b32_e32 v37, 11, v37
	v_add_u32_e32 v38, s62, v36
	v_lshl_add_u32 v20, v38, 1, v37
	s_mov_b32 s57, -1
	s_mov_b32 s69, 0
	s_mov_b32 s67, 0
	s_waitcnt vmcnt(0)
	s_add_u32 s60, s28, s67
	s_addc_u32 s61, s29, 0
	global_load_dwordx2 v[44:45], v12, s[60:61]
	global_load_dwordx2 v[52:53], v13, s[60:61]
	s_add_u32 s60, s34, s67
	s_addc_u32 s61, s35, 0
	global_load_dwordx2 v[46:47], v12, s[60:61]
	global_load_dwordx2 v[54:55], v13, s[60:61]
	s_add_u32 s60, s30, s67
	s_addc_u32 s61, s31, 0
	global_load_dwordx4 v[48:51], v14, s[60:61]
	global_load_dwordx4 v[56:59], v15, s[60:61]
	s_mov_b32 s67, 0x8000
	s_add_u32 s60, s28, s67
	s_addc_u32 s61, s29, 0
	global_load_dwordx2 v[60:61], v12, s[60:61]
	global_load_dwordx2 v[68:69], v13, s[60:61]
	s_add_u32 s60, s34, s67
	s_addc_u32 s61, s35, 0
	global_load_dwordx2 v[62:63], v12, s[60:61]
	global_load_dwordx2 v[70:71], v13, s[60:61]
	s_add_u32 s60, s30, s67
	s_addc_u32 s61, s31, 0
	global_load_dwordx4 v[64:67], v14, s[60:61]
	global_load_dwordx4 v[72:75], v15, s[60:61]
.Lflush_loop:
.Lflush_half_0:
	s_cmp_gt_i32 s57, 0x1fe
	s_cbranch_scc1 .Lflush_y_0
	v_mov_b32_e32 v22, v2
	s_cmp_gt_i32 s57, 0x1fd
	s_cbranch_scc1 .Lflush_w0_0
	s_waitcnt vmcnt(6)
	s_branch .Lflush_wd_0

; #define LAS __attribute__((address_space(3)))
; DI void rwkv_scan_phase(int wv, const Params& P, LAS unsigned char* lds) {
;     ...
;                     if (ck >= 1) { const LAS float* yb = ybuf + ((ck - 1) & 1) * RW_T * 128;
; #pragma unroll 2
;                         for (int it = pw; it < 64; it += 6) { const float y = row16_sum(yb[it * 64 + lane]);
;                             const float y0 = __builtin_bit_cast(float, __builtin_amdgcn_readlane(__builtin_bit_cast(int, y), 0)), y1 = __builtin_bit_cast(float, __builtin_amdgcn_readlane(__builtin_bit_cast(int, y), 16)),
;                                         y2 = __builtin_bit_cast(float, __builtin_amdgcn_readlane(__builtin_bit_cast(int, y), 32)), y3 = __builtin_bit_cast(float, __builtin_amdgcn_readlane(__builtin_bit_cast(int, y), 48));
;                             if (lane == 0) { u32x2 w; w.x = pk2(y0, y1); w.y = pk2(y2, y3); *(u32x2*)(YS + ((size_t)b * SEQ + (ck - 1) * RW_T + (it >> 1)) * 1024 + h * 64 + rg * 8 + (it & 1) * 4) = w; } } }
;                     if (ck + 1 < nck) { const int cn = ck + 1, buf = cn & 1;
; #pragma unroll
;                         for (int i = 0; i < 3; ++i) { const int pp = pw + 6 * i; if (pp < 16) { const int tt = 2 * pp + hf; const size_t row = (size_t)b * SEQ + cn * RW_T + tt;
;                             const f32x2 k = {bflo(gk[i]), bfhi(gk[i])}, a = {bflo(ga[i]), bfhi(ga[i])}, r = {bflo(gr[i]), bfhi(gr[i])};
;                             const h16x2 lh = __builtin_bit_cast(h16x2, gl[i]);
;                             const f32x2 kr = k * kkw2, kp = k * ((a - 1.f) * kaw2 + 1.f);
;                             const float sp = kr[0] * kr[0] + kr[1] * kr[1], rp = r[0] * kp[0] * rkw2[0] + r[1] * kp[1] * rkw2[1];
;                             const bool odd = lane & 1;
;                             float red = (odd ? rp : sp) + dpp_f<0xB1>(odd ? sp : rp);
;                             red += dpp_f<0x4E>(red); red += dpp_f<0x124>(red); red += dpp_f<0x128>(red);
;                             { auto x = __builtin_amdgcn_permlane16_swap(__float_as_uint(red), __float_as_uint(red), false, false); red = __uint_as_float(x[0]) + __uint_as_float(x[1]); }
;                             const float oth = dpp_f<0xB1>(red); const float ss = odd ? oth : red, rks = odd ? red : oth;
;                             const f32x2 kk = kr * __builtin_amdgcn_rsqf(fmaxf(ss, 1e-24f));
.Lflush_wd_0:
	v_lshlrev_b32_e32 v24, 16, v46
	v_and_b32_e32 v25, 0xffff0000, v46
	v_lshlrev_b32_e32 v26, 16, v47
	v_and_b32_e32 v27, 0xffff0000, v47
	v_lshlrev_b32_e32 v28, 16, v44
	v_and_b32_e32 v29, 0xffff0000, v44
	v_pk_add_f32 v[24:25], v[24:25], -1.0 op_sel_hi:[1,0]
	v_lshlrev_b32_e32 v30, 16, v45
	v_pk_add_f32 v[26:27], v[26:27], -1.0 op_sel_hi:[1,0]
	v_and_b32_e32 v31, 0xffff0000, v45
	v_pk_fma_f32 v[24:25], v[4:5], v[24:25], 1.0 op_sel_hi:[1,1,0]
	v_lshlrev_b32_e32 v32, 16, v48
	v_pk_fma_f32 v[26:27], v[6:7], v[26:27], 1.0 op_sel_hi:[1,1,0]
	v_and_b32_e32 v33, 0xffff0000, v48
	v_pk_mul_f32 v[28:29], v[24:25], v[28:29]
	s_nop 0
	v_pk_mul_f32 v[30:31], v[26:27], v[30:31]
	s_nop 0
	v_pk_mul_f32 v[36:37], v[28:29], v[32:33] op_sel_hi:[1,0]
	v_pk_mul_f32 v[38:39], v[30:31], v[32:33] op_sel_hi:[1,0]
	v_pk_mul_f32 v[76:77], v[28:29], v[32:33] op_sel:[0,1] op_sel_hi:[1,1]
	v_pk_mul_f32 v[78:79], v[30:31], v[32:33] op_sel:[0,1] op_sel_hi:[1,1]
	v_lshlrev_b32_e32 v32, 16, v49
	v_and_b32_e32 v33, 0xffff0000, v49
	ds_write_b128 v22, v[36:39] offset:0
	ds_write_b128 v22, v[76:79] offset:256
	v_pk_mul_f32 v[8:9], v[28:29], v[32:33] op_sel_hi:[1,0]
	v_pk_mul_f32 v[10:11], v[30:31], v[32:33] op_sel_hi:[1,0]
	v_pk_mul_f32 v[16:17], v[28:29], v[32:33] op_sel:[0,1] op_sel_hi:[1,1]
	v_pk_mul_f32 v[18:19], v[30:31], v[32:33] op_sel:[0,1] op_sel_hi:[1,1]
	v_lshlrev_b32_e32 v32, 16, v50
	v_and_b32_e32 v33, 0xffff0000, v50
	ds_write_b128 v22, v[8:11] offset:512
	ds_write_b128 v22, v[16:19] offset:768
	v_pk_mul_f32 v[36:37], v[28:29], v[32:33] op_sel_hi:[1,0]
	v_pk_mul_f32 v[38:39], v[30:31], v[32:33] op_sel_hi:[1,0]
	v_pk_mul_f32 v[76:77], v[28:29], v[32:33] op_sel:[0,1] op_sel_hi:[1,1]
	v_pk_mul_f32 v[78:79], v[30:31], v[32:33] op_sel:[0,1] op_sel_hi:[1,1]
	v_lshlrev_b32_e32 v32, 16, v51
	v_and_b32_e32 v33, 0xffff0000, v51
	ds_write_b128 v22, v[36:39] offset:1024
	ds_write_b128 v22, v[76:79] offset:1280
	v_pk_mul_f32 v[8:9], v[28:29], v[32:33] op_sel_hi:[1,0]
	v_pk_mul_f32 v[10:11], v[30:31], v[32:33] op_sel_hi:[1,0]
	v_pk_mul_f32 v[16:17], v[28:29], v[32:33] op_sel:[0,1] op_sel_hi:[1,1]
	v_pk_mul_f32 v[18:19], v[30:31], v[32:33] op_sel:[0,1] op_sel_hi:[1,1]
	s_nop 0
	ds_write_b128 v22, v[8:11] offset:1536
	ds_write_b128 v22, v[16:19] offset:1792
	v_lshlrev_b32_e32 v24, 16, v54
	v_and_b32_e32 v25, 0xffff0000, v54
	v_lshlrev_b32_e32 v26, 16, v55
	v_and_b32_e32 v27, 0xffff0000, v55
	v_lshlrev_b32_e32 v28, 16, v52
	v_and_b32_e32 v29, 0xffff0000, v52
	v_pk_add_f32 v[24:25], v[24:25], -1.0 op_sel_hi:[1,0]
	v_lshlrev_b32_e32 v30, 16, v53
	v_pk_add_f32 v[26:27], v[26:27], -1.0 op_sel_hi:[1,0]
	v_and_b32_e32 v31, 0xffff0000, v53
	v_pk_fma_f32 v[24:25], v[4:5], v[24:25], 1.0 op_sel_hi:[1,1,0]
	v_lshlrev_b32_e32 v32, 16, v56
	v_pk_fma_f32 v[26:27], v[6:7], v[26:27], 1.0 op_sel_hi:[1,1,0]
	v_and_b32_e32 v33, 0xffff0000, v56
	v_pk_mul_f32 v[28:29], v[24:25], v[28:29]
	s_nop 0
	v_pk_mul_f32 v[30:31], v[26:27], v[30:31]
	s_nop 0
	v_pk_mul_f32 v[36:37], v[28:29], v[32:33] op_sel_hi:[1,0]
	v_pk_mul_f32 v[38:39], v[30:31], v[32:33] op_sel_hi:[1,0]
	v_pk_mul_f32 v[76:77], v[28:29], v[32:33] op_sel:[0,1] op_sel_hi:[1,1]
	v_pk_mul_f32 v[78:79], v[30:31], v[32:33] op_sel:[0,1] op_sel_hi:[1,1]
	v_lshlrev_b32_e32 v32, 16, v57
	v_and_b32_e32 v33, 0xffff0000, v57
	ds_write_b128 v22, v[36:39] offset:12288
	ds_write_b128 v22, v[76:79] offset:12544
	v_pk_mul_f32 v[8:9], v[28:29], v[32:33] op_sel_hi:[1,0]
	v_pk_mul_f32 v[10:11], v[30:31], v[32:33] op_sel_hi:[1,0]
	v_pk_mul_f32 v[16:17], v[28:29], v[32:33] op_sel:[0,1] op_sel_hi:[1,1]
	v_pk_mul_f32 v[18:19], v[30:31], v[32:33] op_sel:[0,1] op_sel_hi:[1,1]
	v_lshlrev_b32_e32 v32, 16, v58
	v_and_b32_e32 v33, 0xffff0000, v58
	ds_write_b128 v22, v[8:11] offset:12800
	ds_write_b128 v22, v[16:19] offset:13056
	v_pk_mul_f32 v[36:37], v[28:29], v[32:33] op_sel_hi:[1,0]
	v_pk_mul_f32 v[38:39], v[30:31], v[32:33] op_sel_hi:[1,0]
	v_pk_mul_f32 v[76:77], v[28:29], v[32:33] op_sel:[0,1] op_sel_hi:[1,1]
	v_pk_mul_f32 v[78:79], v[30:31], v[32:33] op_sel:[0,1] op_sel_hi:[1,1]
	v_lshlrev_b32_e32 v32, 16, v59
	v_and_b32_e32 v33, 0xffff0000, v59
	ds_write_b128 v22, v[36:39] offset:13312
	ds_write_b128 v22, v[76:79] offset:13568
	v_pk_mul_f32 v[8:9], v[28:29], v[32:33] op_sel_hi:[1,0]
	v_pk_mul_f32 v[10:11], v[30:31], v[32:33] op_sel_hi:[1,0]
	v_pk_mul_f32 v[16:17], v[28:29], v[32:33] op_sel:[0,1] op_sel_hi:[1,1]
	v_pk_mul_f32 v[18:19], v[30:31], v[32:33] op_sel:[0,1] op_sel_hi:[1,1]
	s_nop 0
	ds_write_b128 v22, v[8:11] offset:13824
	ds_write_b128 v22, v[16:19] offset:14080
.Lflush_y_0:
	s_cmp_lt_i32 s57, 2
	s_cbranch_scc1 .Lflush_ld_0
	v_add_u32_e32 v21, s69, v3
	s_add_i32 s69, s69, 0x2000
	s_cmp_eq_u32 s69, 0x6000
	s_cselect_b32 s69, 0, s69
	ds_read_b128 v[24:27], v21
	ds_read_b128 v[28:31], v21 offset:16
	ds_read_b128 v[32:35], v21 offset:32
	ds_read_b128 v[36:39], v21 offset:48
	s_add_i32 s67, s57, -2
	s_lshl_b32 s67, s67, 15
	s_add_u32 s60, s44, s67
	s_addc_u32 s61, s45, 0
	s_waitcnt lgkmcnt(0)
	v_pk_add_f32 v[24:25], v[24:25], v[26:27]
	v_pk_add_f32 v[28:29], v[28:29], v[30:31]
	v_pk_add_f32 v[32:33], v[32:33], v[34:35]
	v_pk_add_f32 v[36:37], v[36:37], v[38:39]
	v_pk_add_f32 v[24:25], v[24:25], v[28:29]
	v_pk_add_f32 v[32:33], v[32:33], v[36:37]
	s_nop 0
	v_pk_add_f32 v[24:25], v[24:25], v[32:33]
	s_nop 0
	v_add_f32_e32 v24, v24, v25
	s_nop 1
	v_mov_b32_dpp v25, v24 quad_perm:[1,0,3,2] row_mask:0xf bank_mask:0xf bound_ctrl:1
	s_nop 0
	v_cvt_pk_bf16_f32 v24, v24, v25
	s_mov_b64 exec, s[8:9]
	global_store_dword v20, v24, s[60:61]
	s_mov_b64 exec, -1
.Lflush_ld_0:
	s_cmp_gt_i32 s57, 0x1fc
	s_cbranch_scc1 .Lflush_sync_0
	s_add_i32 s67, s57, 3
	s_lshl_b32 s67, s67, 15
	s_add_u32 s60, s28, s67
	s_addc_u32 s61, s29, 0
	global_load_dwordx2 v[44:45], v12, s[60:61]
	global_load_dwordx2 v[52:53], v13, s[60:61]
	s_add_u32 s60, s34, s67
	s_addc_u32 s61, s35, 0
	global_load_dwordx2 v[46:47], v12, s[60:61]
	global_load_dwordx2 v[54:55], v13, s[60:61]
	s_add_u32 s60, s30, s67
	s_addc_u32 s61, s31, 0
	global_load_dwordx4 v[48:51], v14, s[60:61]
	global_load_dwordx4 v[56:59], v15, s[60:61]

; DI void rwkv_scan_phase(int wv, const Params& P, LAS unsigned char* lds) {
;     ...
;                     if (ck + 1 < nck) { const int cn = ck + 1, buf = cn & 1;
; #pragma unroll
;                         for (int i = 0; i < 3; ++i) { const int pp = pw + 6 * i; if (pp < 16) { const int tt = 2 * pp + hf; const size_t row = (size_t)b * SEQ + cn * RW_T + tt;
.Lflush_half_1:
	s_cmp_gt_i32 s57, 0x1fe
	s_cbranch_scc1 .Lflush_y_1
	v_add_u32_e32 v22, 0xc000, v2
	s_cmp_gt_i32 s57, 0x1fd
	s_cbranch_scc1 .Lflush_w0_1
	s_waitcnt vmcnt(6)
	s_branch .Lflush_wd_1

; #define LAS __attribute__((address_space(3)))
; DI float bflo(unsigned u) { return __uint_as_float(u << 16); }
; DI float bfhi(unsigned u) { return __uint_as_float(u & 0xffff0000u); }
; template <int CTRL> DI float dpp_f(float v) { return __builtin_bit_cast(float, __builtin_amdgcn_update_dpp(0, __builtin_bit_cast(int, v), CTRL, 0xf, 0xf, true)); }
; DI void rwkv_scan_phase(int wv, const Params& P, LAS unsigned char* lds) {
;     ...
;                             const f32x2 k = {bflo(gk[i]), bfhi(gk[i])}, a = {bflo(ga[i]), bfhi(ga[i])}, r = {bflo(gr[i]), bfhi(gr[i])};
;                             const h16x2 lh = __builtin_bit_cast(h16x2, gl[i]);
;                             const f32x2 kr = k * kkw2, kp = k * ((a - 1.f) * kaw2 + 1.f);
;                             const float sp = kr[0] * kr[0] + kr[1] * kr[1], rp = r[0] * kp[0] * rkw2[0] + r[1] * kp[1] * rkw2[1];
;                             const bool odd = lane & 1;
;                             float red = (odd ? rp : sp) + dpp_f<0xB1>(odd ? sp : rp);
;                             red += dpp_f<0x4E>(red); red += dpp_f<0x124>(red); red += dpp_f<0x128>(red);
;                             { auto x = __builtin_amdgcn_permlane16_swap(__float_as_uint(red), __float_as_uint(red), false, false); red = __uint_as_float(x[0]) + __uint_as_float(x[1]); }
;                             const float oth = dpp_f<0xB1>(red); const float ss = odd ? oth : red, rks = odd ? red : oth;
;                             const f32x2 kk = kr * __builtin_amdgcn_rsqf(fmaxf(ss, 1e-24f));
;                             LAS float* d = stg + ((buf * RW_T + tt) * 5) * 64 + 2 * c2;
;                             *(LAS f32x2*)(d) = -kk; *(LAS f32x2*)(d + 64) = (f32x2){__expf((float)lh[0]), __expf((float)lh[1])}; *(LAS f32x2*)(d + 128) = kk * a; *(LAS f32x2*)(d + 192) = kp; *(LAS f32x2*)(d + 256) = r;
.Lflush_wd_1:
	v_lshlrev_b32_e32 v24, 16, v62
	v_and_b32_e32 v25, 0xffff0000, v62
	v_lshlrev_b32_e32 v26, 16, v63
	v_and_b32_e32 v27, 0xffff0000, v63
	v_lshlrev_b32_e32 v28, 16, v60
	v_and_b32_e32 v29, 0xffff0000, v60
	v_pk_add_f32 v[24:25], v[24:25], -1.0 op_sel_hi:[1,0]
	v_lshlrev_b32_e32 v30, 16, v61
	v_pk_add_f32 v[26:27], v[26:27], -1.0 op_sel_hi:[1,0]
	v_and_b32_e32 v31, 0xffff0000, v61
	v_pk_fma_f32 v[24:25], v[4:5], v[24:25], 1.0 op_sel_hi:[1,1,0]
	v_lshlrev_b32_e32 v32, 16, v64
	v_pk_fma_f32 v[26:27], v[6:7], v[26:27], 1.0 op_sel_hi:[1,1,0]
	v_and_b32_e32 v33, 0xffff0000, v64
	v_pk_mul_f32 v[28:29], v[24:25], v[28:29]
	s_nop 0
	v_pk_mul_f32 v[30:31], v[26:27], v[30:31]
	s_nop 0
	v_pk_mul_f32 v[36:37], v[28:29], v[32:33] op_sel_hi:[1,0]
	v_pk_mul_f32 v[38:39], v[30:31], v[32:33] op_sel_hi:[1,0]
	v_pk_mul_f32 v[76:77], v[28:29], v[32:33] op_sel:[0,1] op_sel_hi:[1,1]
	v_pk_mul_f32 v[78:79], v[30:31], v[32:33] op_sel:[0,1] op_sel_hi:[1,1]
	v_lshlrev_b32_e32 v32, 16, v65
	v_and_b32_e32 v33, 0xffff0000, v65
	ds_write_b128 v22, v[36:39] offset:0
	ds_write_b128 v22, v[76:79] offset:256
	v_pk_mul_f32 v[8:9], v[28:29], v[32:33] op_sel_hi:[1,0]
	v_pk_mul_f32 v[10:11], v[30:31], v[32:33] op_sel_hi:[1,0]
	v_pk_mul_f32 v[16:17], v[28:29], v[32:33] op_sel:[0,1] op_sel_hi:[1,1]
	v_pk_mul_f32 v[18:19], v[30:31], v[32:33] op_sel:[0,1] op_sel_hi:[1,1]
	v_lshlrev_b32_e32 v32, 16, v66
	v_and_b32_e32 v33, 0xffff0000, v66
	ds_write_b128 v22, v[8:11] offset:512
	ds_write_b128 v22, v[16:19] offset:768
	v_pk_mul_f32 v[36:37], v[28:29], v[32:33] op_sel_hi:[1,0]
	v_pk_mul_f32 v[38:39], v[30:31], v[32:33] op_sel_hi:[1,0]
	v_pk_mul_f32 v[76:77], v[28:29], v[32:33] op_sel:[0,1] op_sel_hi:[1,1]
	v_pk_mul_f32 v[78:79], v[30:31], v[32:33] op_sel:[0,1] op_sel_hi:[1,1]
	v_lshlrev_b32_e32 v32, 16, v67
	v_and_b32_e32 v33, 0xffff0000, v67
	ds_write_b128 v22, v[36:39] offset:1024
	ds_write_b128 v22, v[76:79] offset:1280
	v_pk_mul_f32 v[8:9], v[28:29], v[32:33] op_sel_hi:[1,0]
	v_pk_mul_f32 v[10:11], v[30:31], v[32:33] op_sel_hi:[1,0]
	v_pk_mul_f32 v[16:17], v[28:29], v[32:33] op_sel:[0,1] op_sel_hi:[1,1]
	v_pk_mul_f32 v[18:19], v[30:31], v[32:33] op_sel:[0,1] op_sel_hi:[1,1]
	s_nop 0
	ds_write_b128 v22, v[8:11] offset:1536
	ds_write_b128 v22, v[16:19] offset:1792
	v_lshlrev_b32_e32 v24, 16, v70
	v_and_b32_e32 v25, 0xffff0000, v70
	v_lshlrev_b32_e32 v26, 16, v71
	v_and_b32_e32 v27, 0xffff0000, v71
	v_lshlrev_b32_e32 v28, 16, v68
	v_and_b32_e32 v29, 0xffff0000, v68
	v_pk_add_f32 v[24:25], v[24:25], -1.0 op_sel_hi:[1,0]
	v_lshlrev_b32_e32 v30, 16, v69
	v_pk_add_f32 v[26:27], v[26:27], -1.0 op_sel_hi:[1,0]
	v_and_b32_e32 v31, 0xffff0000, v69
	v_pk_fma_f32 v[24:25], v[4:5], v[24:25], 1.0 op_sel_hi:[1,1,0]
	v_lshlrev_b32_e32 v32, 16, v72
	v_pk_fma_f32 v[26:27], v[6:7], v[26:27], 1.0 op_sel_hi:[1,1,0]
	v_and_b32_e32 v33, 0xffff0000, v72
	v_pk_mul_f32 v[28:29], v[24:25], v[28:29]
	s_nop 0
	v_pk_mul_f32 v[30:31], v[26:27], v[30:31]
	s_nop 0
	v_pk_mul_f32 v[36:37], v[28:29], v[32:33] op_sel_hi:[1,0]
	v_pk_mul_f32 v[38:39], v[30:31], v[32:33] op_sel_hi:[1,0]
	v_pk_mul_f32 v[76:77], v[28:29], v[32:33] op_sel:[0,1] op_sel_hi:[1,1]
	v_pk_mul_f32 v[78:79], v[30:31], v[32:33] op_sel:[0,1] op_sel_hi:[1,1]
	v_lshlrev_b32_e32 v32, 16, v73
	v_and_b32_e32 v33, 0xffff0000, v73
	ds_write_b128 v22, v[36:39] offset:12288
	ds_write_b128 v22, v[76:79] offset:12544
	v_pk_mul_f32 v[8:9], v[28:29], v[32:33] op_sel_hi:[1,0]
	v_pk_mul_f32 v[10:11], v[30:31], v[32:33] op_sel_hi:[1,0]
	v_pk_mul_f32 v[16:17], v[28:29], v[32:33] op_sel:[0,1] op_sel_hi:[1,1]
	v_pk_mul_f32 v[18:19], v[30:31], v[32:33] op_sel:[0,1] op_sel_hi:[1,1]
	v_lshlrev_b32_e32 v32, 16, v74
	v_and_b32_e32 v33, 0xffff0000, v74
	ds_write_b128 v22, v[8:11] offset:12800
	ds_write_b128 v22, v[16:19] offset:13056
	v_pk_mul_f32 v[36:37], v[28:29], v[32:33] op_sel_hi:[1,0]
	v_pk_mul_f32 v[38:39], v[30:31], v[32:33] op_sel_hi:[1,0]
	v_pk_mul_f32 v[76:77], v[28:29], v[32:33] op_sel:[0,1] op_sel_hi:[1,1]
	v_pk_mul_f32 v[78:79], v[30:31], v[32:33] op_sel:[0,1] op_sel_hi:[1,1]
	v_lshlrev_b32_e32 v32, 16, v75
	v_and_b32_e32 v33, 0xffff0000, v75
	ds_write_b128 v22, v[36:39] offset:13312
	ds_write_b128 v22, v[76:79] offset:13568
	v_pk_mul_f32 v[8:9], v[28:29], v[32:33] op_sel_hi:[1,0]
	v_pk_mul_f32 v[10:11], v[30:31], v[32:33] op_sel_hi:[1,0]
	v_pk_mul_f32 v[16:17], v[28:29], v[32:33] op_sel:[0,1] op_sel_hi:[1,1]
	v_pk_mul_f32 v[18:19], v[30:31], v[32:33] op_sel:[0,1] op_sel_hi:[1,1]
	s_nop 0
	ds_write_b128 v22, v[8:11] offset:13824
	ds_write_b128 v22, v[16:19] offset:14080

; DI void rwkv_scan_phase(int wv, const Params& P, LAS unsigned char* lds) {
;     ...
;             RW_LOADG(0)
; #pragma unroll 1
;             for (int ck = -1; ck <= nck; ++ck) {
;                 {
;                     if (ck >= 1) { const LAS float* yb = ybuf + ((ck - 1) & 1) * RW_T * 128;
; #pragma unroll 2
;                         for (int it = pw; it < 64; it += 6) { const float y = row16_sum(yb[it * 64 + lane]);
;                             const float y0 = __builtin_bit_cast(float, __builtin_amdgcn_readlane(__builtin_bit_cast(int, y), 0)), y1 = __builtin_bit_cast(float, __builtin_amdgcn_readlane(__builtin_bit_cast(int, y), 16)),
;                                         y2 = __builtin_bit_cast(float, __builtin_amdgcn_readlane(__builtin_bit_cast(int, y), 32)), y3 = __builtin_bit_cast(float, __builtin_amdgcn_readlane(__builtin_bit_cast(int, y), 48));
;                             if (lane == 0) { u32x2 w; w.x = pk2(y0, y1); w.y = pk2(y2, y3); *(u32x2*)(YS + ((size_t)b * SEQ + (ck - 1) * RW_T + (it >> 1)) * 1024 + h * 64 + rg * 8 + (it & 1) * 4) = w; } } }
;                     if (ck + 1 < nck) { const int cn = ck + 1, buf = cn & 1;
; #pragma unroll
;                         for (int i = 0; i < 3; ++i) { const int pp = pw + 6 * i; if (pp < 16) { const int tt = 2 * pp + hf; const size_t row = (size_t)b * SEQ + cn * RW_T + tt;
;                             const f32x2 k = {bflo(gk[i]), bfhi(gk[i])}, a = {bflo(ga[i]), bfhi(ga[i])}, r = {bflo(gr[i]), bfhi(gr[i])};
;                             const h16x2 lh = __builtin_bit_cast(h16x2, gl[i]);
;                             const f32x2 kr = k * kkw2, kp = k * ((a - 1.f) * kaw2 + 1.f);
;                             const float sp = kr[0] * kr[0] + kr[1] * kr[1], rp = r[0] * kp[0] * rkw2[0] + r[1] * kp[1] * rkw2[1];
;                             const bool odd = lane & 1;
;                             float red = (odd ? rp : sp) + dpp_f<0xB1>(odd ? sp : rp);
;                             red += dpp_f<0x4E>(red); red += dpp_f<0x124>(red); red += dpp_f<0x128>(red);
;                             { auto x = __builtin_amdgcn_permlane16_swap(__float_as_uint(red), __float_as_uint(red), false, false); red = __uint_as_float(x[0]) + __uint_as_float(x[1]); }
;                             const float oth = dpp_f<0xB1>(red); const float ss = odd ? oth : red, rks = odd ? red : oth;
.Lflush_ld_1:
	s_cmp_gt_i32 s57, 0x1fc
	s_cbranch_scc1 .Lflush_sync_1
	s_add_i32 s67, s57, 3
	s_lshl_b32 s67, s67, 15
	s_add_u32 s60, s28, s67
	s_addc_u32 s61, s29, 0
	global_load_dwordx2 v[60:61], v12, s[60:61]
	global_load_dwordx2 v[68:69], v13, s[60:61]
	s_add_u32 s60, s34, s67
	s_addc_u32 s61, s35, 0
	global_load_dwordx2 v[62:63], v12, s[60:61]
	global_load_dwordx2 v[70:71], v13, s[60:61]
	s_add_u32 s60, s30, s67
	s_addc_u32 s61, s31, 0
	global_load_dwordx4 v[64:67], v14, s[60:61]
	global_load_dwordx4 v[72:75], v15, s[60:61]
